# K-loops: the pad slot between each M0 write and its LDS-DMA load now holds one of the segment's ds_read_b128 instead of s_nop
# baseline (speedup 1.0000x reference)
; #define PG8_STAGE(bufoff, gbase, voff) do { _Pragma("unroll") for (int _i = 0; _i < 2; ++_i) \
;         __builtin_amdgcn_global_load_lds((const unsigned*)((const char*)(gbase) + (voff)[_i]), (PG8_LAS unsigned*)(lds + (bufoff) + ldsw + _i * 8192), 16, 0, 0); } while (0)
; #define PG8_LDA(dst, b, h) do { _Pragma("unroll") for (int m = 0; m < 4; ++m) _Pragma("unroll") for (int k = 0; k < 2; ++k) dst[m][k] = *(const PG8_LAS bf16x8*)(lds + PG8_SA(b, h) + aoff + m * 2048 + k * 1024); } while (0)
; #define PG8_LDB(dst, b, h) do { _Pragma("unroll") for (int n = 0; n < 2; ++n) _Pragma("unroll") for (int k = 0; k < 2; ++k) dst[n][k] = *(const PG8_LAS bf16x8*)(lds + PG8_SB(b, h) + boff + n * 2048 + k * 1024); } while (0)
; #define PG8_MMA(ai, bj, At, Bt) do { __builtin_amdgcn_s_setprio(1); _Pragma("unroll") for (int m = 0; m < 4; ++m) _Pragma("unroll") for (int n = 0; n < 2; ++n) _Pragma("unroll") for (int k = 0; k < 2; ++k) \
;         acc[ai][bj][m][n] = __builtin_amdgcn_mfma_f32_16x16x32_bf16(Bt[n][k], At[m][k], acc[ai][bj][m][n], 0, 0, 0); __builtin_amdgcn_s_setprio(0); } while (0)
; #define PG8_WAIT_V(n) asm volatile("s_waitcnt vmcnt(" #n ")" ::: "memory")
; #define PG8_WAIT_L(n) asm volatile("s_waitcnt lgkmcnt(" #n ")" ::: "memory")
; template <class Epi, class Sched, bool ALIGN_EPI = false, bool SP2 = false>
; __device__ __forceinline__ void gemm_phase(PG8_LAS unsigned char* lds, const Gemm g, const Sched& S, const Epi& E, int wave_in) {
;     ...
;             const bool last = (t == nt - 2);
;             const char* a1 = cA + (size_t)(t + 1) * kstep;
;             const char* a2 = last ? nA : cA + (size_t)(t + 2) * kstep; const char* b2 = last ? nB : cB + (size_t)(t + 2) * kstep;
;             const char* a3 = a2 + kstep; const char* b3 = b2 + kstep;
;             if (last && has_next) S.a_ready(nxt);
;             if constexpr (SP2) {
;             PG8_LDB(B0, 0, 0); PG8_LDB(B1, 0, 1); PG8_SCHED; PG8_LDA(At, 0, 0); PG8_STAGE(PG8_SA(1, 1), a1 + hstepA, voffA);
;             PG8_WAIT_V(8); PG8_WAIT_L(0); PG8_BAR; PG8_MMA(0, 0, At, B0); PG8_MMA(0, 1, At, B1); PG8_BAR; PG8_SCHED;
;             PG8_LDA(At, 0, 1); PG8_STAGE(PG8_SB(0, 0), b2, voffB); PG8_STAGE(PG8_SB(0, 1), b2 + hstep, voffB); PG8_STAGE(PG8_SA(0, 0), a2, voffA);
;             PG8_WAIT_V(8); PG8_WAIT_L(0); PG8_BAR; PG8_MMA(1, 0, At, B0); PG8_MMA(1, 1, At, B1); PG8_BAR; PG8_SCHED;
.LBB0_43:
	s_add_u32 s50, s48, 0xfff80080
	s_addc_u32 s51, s49, -1
	s_add_i32 s72, 0, 0x10000
	s_cmp_eq_u32 s71, 28
	s_cselect_b32 s53, s43, s51
	s_cselect_b32 s52, s67, s50
	s_cselect_b32 s51, s41, s70
	s_cselect_b32 s50, s68, s69
	s_add_i32 s74, 0, 0x14000
	v_add_u32_e32 v118, s72, v214
	v_add_u32_e32 v178, s74, v214
	ds_read_b128 v[106:109], v118
	ds_read_b128 v[110:113], v118 offset:1024
	ds_read_b128 v[114:117], v118 offset:2048
	ds_read_b128 v[118:121], v118 offset:3072
	ds_read_b128 v[122:125], v178
	ds_read_b128 v[126:129], v178 offset:1024
	ds_read_b128 v[130:133], v178 offset:2048
	ds_read_b128 v[178:181], v178 offset:3072
	s_add_i32 m0, s58, 0xc000
	ds_read_b128 v[182:185], v217
	ds_read_b128 v[186:189], v217 offset:1024
	ds_read_b128 v[190:193], v217 offset:2048
	ds_read_b128 v[218:221], v217 offset:3072
	ds_read_b128 v[222:225], v217 offset:4096
	ds_read_b128 v[226:229], v217 offset:5120
	ds_read_b128 v[230:233], v217 offset:6144
	global_load_lds_dwordx4 v174, s[48:49]
	s_add_i32 m0, s58, 0xe000
	ds_read_b128 v[234:237], v217 offset:7168
	global_load_lds_dwordx4 v176, s[48:49]
	s_waitcnt vmcnt(8)
	s_waitcnt lgkmcnt(0)
	s_barrier
	s_waitcnt lgkmcnt(0)
	v_mfma_f32_16x16x32_bf16 v[154:157], v[106:109], v[182:185], v[154:157]
	v_mfma_f32_16x16x32_bf16 v[62:65], v[114:117], v[182:185], v[62:65]
	v_mfma_f32_16x16x32_bf16 v[150:153], v[106:109], v[190:193], v[150:153]
	v_mfma_f32_16x16x32_bf16 v[54:57], v[114:117], v[190:193], v[54:57]
	v_mfma_f32_16x16x32_bf16 v[142:145], v[106:109], v[222:225], v[142:145]
	v_mfma_f32_16x16x32_bf16 v[46:49], v[114:117], v[222:225], v[46:49]
	v_mfma_f32_16x16x32_bf16 v[102:105], v[106:109], v[230:233], v[102:105]
	v_mfma_f32_16x16x32_bf16 v[38:41], v[114:117], v[230:233], v[38:41]
	v_mfma_f32_16x16x32_bf16 v[154:157], v[110:113], v[186:189], v[154:157]
	v_mfma_f32_16x16x32_bf16 v[62:65], v[118:121], v[186:189], v[62:65]
	v_mfma_f32_16x16x32_bf16 v[150:153], v[110:113], v[218:221], v[150:153]
	v_mfma_f32_16x16x32_bf16 v[54:57], v[118:121], v[218:221], v[54:57]
	v_mfma_f32_16x16x32_bf16 v[142:145], v[110:113], v[226:229], v[142:145]
	v_mfma_f32_16x16x32_bf16 v[46:49], v[118:121], v[226:229], v[46:49]
	v_mfma_f32_16x16x32_bf16 v[102:105], v[110:113], v[234:237], v[102:105]
	v_mfma_f32_16x16x32_bf16 v[38:41], v[118:121], v[234:237], v[38:41]
	v_mfma_f32_16x16x32_bf16 v[134:137], v[122:125], v[182:185], v[134:137]
	v_mfma_f32_16x16x32_bf16 v[58:61], v[130:133], v[182:185], v[58:61]
	v_mfma_f32_16x16x32_bf16 v[146:149], v[122:125], v[190:193], v[146:149]
	v_mfma_f32_16x16x32_bf16 v[50:53], v[130:133], v[190:193], v[50:53]
	v_mfma_f32_16x16x32_bf16 v[138:141], v[122:125], v[222:225], v[138:141]
	v_mfma_f32_16x16x32_bf16 v[42:45], v[130:133], v[222:225], v[42:45]
	v_mfma_f32_16x16x32_bf16 v[98:101], v[122:125], v[230:233], v[98:101]
	v_mfma_f32_16x16x32_bf16 v[34:37], v[130:133], v[230:233], v[34:37]
	v_mfma_f32_16x16x32_bf16 v[134:137], v[126:129], v[186:189], v[134:137]
	v_mfma_f32_16x16x32_bf16 v[58:61], v[178:181], v[186:189], v[58:61]
	v_mfma_f32_16x16x32_bf16 v[146:149], v[126:129], v[218:221], v[146:149]
	v_mfma_f32_16x16x32_bf16 v[50:53], v[178:181], v[218:221], v[50:53]
	v_mfma_f32_16x16x32_bf16 v[138:141], v[126:129], v[226:229], v[138:141]
	v_mfma_f32_16x16x32_bf16 v[42:45], v[178:181], v[226:229], v[42:45]
	v_mfma_f32_16x16x32_bf16 v[98:101], v[126:129], v[234:237], v[98:101]
	v_mfma_f32_16x16x32_bf16 v[34:37], v[178:181], v[234:237], v[34:37]
	s_barrier
	s_add_i32 s72, s72, s57
	s_add_u32 vcc_lo, s50, s84
	s_addc_u32 vcc_hi, s51, s85
	s_mov_b32 m0, s72
	ds_read_b128 v[182:185], v217 offset:16384
	ds_read_b128 v[186:189], v217 offset:17408
	ds_read_b128 v[190:193], v217 offset:18432
	ds_read_b128 v[218:221], v217 offset:19456
	ds_read_b128 v[222:225], v217 offset:20480
	global_load_lds_dwordx4 v0, s[50:51]
	s_add_i32 m0, s72, 0x2000
	s_add_u32 s72, s50, 0x80000
	s_addc_u32 s73, s51, 0
	s_add_i32 s74, s74, s57
	global_load_lds_dwordx4 v168, s[50:51]
	s_mov_b32 m0, s74
	s_add_u32 s98, s52, s84
	s_addc_u32 s99, s53, s85
	global_load_lds_dwordx4 v0, s[72:73]
	s_add_i32 m0, s74, 0x2000
	ds_read_b128 v[226:229], v217 offset:21504
	global_load_lds_dwordx4 v168, s[72:73]
	s_mov_b32 m0, s58
	ds_read_b128 v[230:233], v217 offset:22528
	global_load_lds_dwordx4 v172, s[52:53]
	s_mov_b32 m0, s59
	ds_read_b128 v[234:237], v217 offset:23552
	global_load_lds_dwordx4 v170, s[52:53]
	s_waitcnt vmcnt(8)
	s_waitcnt lgkmcnt(0)
	s_barrier
	s_waitcnt lgkmcnt(0)
	v_mfma_f32_16x16x32_bf16 v[94:97], v[106:109], v[182:185], v[94:97]
	v_mfma_f32_16x16x32_bf16 v[30:33], v[114:117], v[182:185], v[30:33]
	v_mfma_f32_16x16x32_bf16 v[86:89], v[106:109], v[190:193], v[86:89]
	v_mfma_f32_16x16x32_bf16 v[22:25], v[114:117], v[190:193], v[22:25]
	v_mfma_f32_16x16x32_bf16 v[78:81], v[106:109], v[222:225], v[78:81]
	v_mfma_f32_16x16x32_bf16 v[14:17], v[114:117], v[222:225], v[14:17]
	v_mfma_f32_16x16x32_bf16 v[70:73], v[106:109], v[230:233], v[70:73]
	v_mfma_f32_16x16x32_bf16 v[6:9], v[114:117], v[230:233], v[6:9]
	v_mfma_f32_16x16x32_bf16 v[94:97], v[110:113], v[186:189], v[94:97]
	v_mfma_f32_16x16x32_bf16 v[30:33], v[118:121], v[186:189], v[30:33]
	v_mfma_f32_16x16x32_bf16 v[86:89], v[110:113], v[218:221], v[86:89]
	v_mfma_f32_16x16x32_bf16 v[22:25], v[118:121], v[218:221], v[22:25]
	v_mfma_f32_16x16x32_bf16 v[78:81], v[110:113], v[226:229], v[78:81]
	v_mfma_f32_16x16x32_bf16 v[14:17], v[118:121], v[226:229], v[14:17]
	v_mfma_f32_16x16x32_bf16 v[70:73], v[110:113], v[234:237], v[70:73]
	v_mfma_f32_16x16x32_bf16 v[6:9], v[118:121], v[234:237], v[6:9]
	v_mfma_f32_16x16x32_bf16 v[90:93], v[122:125], v[182:185], v[90:93]
	v_mfma_f32_16x16x32_bf16 v[26:29], v[130:133], v[182:185], v[26:29]
	v_mfma_f32_16x16x32_bf16 v[82:85], v[122:125], v[190:193], v[82:85]
	v_mfma_f32_16x16x32_bf16 v[18:21], v[130:133], v[190:193], v[18:21]
	v_mfma_f32_16x16x32_bf16 v[74:77], v[122:125], v[222:225], v[74:77]
	v_mfma_f32_16x16x32_bf16 v[10:13], v[130:133], v[222:225], v[10:13]
	v_mfma_f32_16x16x32_bf16 v[66:69], v[122:125], v[230:233], v[66:69]
	v_mfma_f32_16x16x32_bf16 v[2:5], v[130:133], v[230:233], v[2:5]
	v_mfma_f32_16x16x32_bf16 v[90:93], v[126:129], v[186:189], v[90:93]
	v_mfma_f32_16x16x32_bf16 v[26:29], v[178:181], v[186:189], v[26:29]
	v_mfma_f32_16x16x32_bf16 v[82:85], v[126:129], v[218:221], v[82:85]
	v_mfma_f32_16x16x32_bf16 v[18:21], v[178:181], v[218:221], v[18:21]
	v_mfma_f32_16x16x32_bf16 v[74:77], v[126:129], v[226:229], v[74:77]
	v_mfma_f32_16x16x32_bf16 v[10:13], v[178:181], v[226:229], v[10:13]
	v_mfma_f32_16x16x32_bf16 v[66:69], v[126:129], v[234:237], v[66:69]
	v_mfma_f32_16x16x32_bf16 v[2:5], v[178:181], v[234:237], v[2:5]
	s_barrier
; #define PG8_STAGE(bufoff, gbase, voff) do { _Pragma("unroll") for (int _i = 0; _i < 2; ++_i) \
;         __builtin_amdgcn_global_load_lds((const unsigned*)((const char*)(gbase) + (voff)[_i]), (PG8_LAS unsigned*)(lds + (bufoff) + ldsw + _i * 8192), 16, 0, 0); } while (0)
; #define PG8_LDA(dst, b, h) do { _Pragma("unroll") for (int m = 0; m < 4; ++m) _Pragma("unroll") for (int k = 0; k < 2; ++k) dst[m][k] = *(const PG8_LAS bf16x8*)(lds + PG8_SA(b, h) + aoff + m * 2048 + k * 1024); } while (0)
; #define PG8_LDB(dst, b, h) do { _Pragma("unroll") for (int n = 0; n < 2; ++n) _Pragma("unroll") for (int k = 0; k < 2; ++k) dst[n][k] = *(const PG8_LAS bf16x8*)(lds + PG8_SB(b, h) + boff + n * 2048 + k * 1024); } while (0)
; #define PG8_MMA(ai, bj, At, Bt) do { __builtin_amdgcn_s_setprio(1); _Pragma("unroll") for (int m = 0; m < 4; ++m) _Pragma("unroll") for (int n = 0; n < 2; ++n) _Pragma("unroll") for (int k = 0; k < 2; ++k) \
;         acc[ai][bj][m][n] = __builtin_amdgcn_mfma_f32_16x16x32_bf16(Bt[n][k], At[m][k], acc[ai][bj][m][n], 0, 0, 0); __builtin_amdgcn_s_setprio(0); } while (0)
; #define PG8_WAIT_V(n) asm volatile("s_waitcnt vmcnt(" #n ")" ::: "memory")
; #define PG8_WAIT_L(n) asm volatile("s_waitcnt lgkmcnt(" #n ")" ::: "memory")
; #define PG8_BAR __builtin_amdgcn_s_barrier()
; #define PG8_SCHED __builtin_amdgcn_sched_barrier(0)
; template <class Epi, class Sched, bool ALIGN_EPI = false, bool SP2 = false>
; __device__ __forceinline__ void gemm_phase(PG8_LAS unsigned char* lds, const Gemm g, const Sched& S, const Epi& E, int wave_in) {
;     ...
;             PG8_LDB(B0, 1, 0); PG8_LDB(B1, 1, 1); PG8_SCHED; PG8_LDA(At, 1, 0); PG8_STAGE(PG8_SA(0, 1), a2 + hstepA, voffA);
;             PG8_WAIT_V(8); PG8_WAIT_L(0); PG8_BAR; PG8_MMA(0, 0, At, B0); PG8_MMA(0, 1, At, B1); PG8_BAR; PG8_SCHED;
;             PG8_LDA(At, 1, 1); PG8_STAGE(PG8_SB(1, 0), b3, voffB); PG8_STAGE(PG8_SB(1, 1), b3 + hstep, voffB); PG8_STAGE(PG8_SA(1, 0), a3, voffA);
;             PG8_WAIT_V(8); PG8_WAIT_L(0); PG8_BAR; PG8_MMA(1, 0, At, B0); PG8_MMA(1, 1, At, B1); PG8_BAR; PG8_SCHED;
	s_add_i32 s72, 0, 0x18000
	s_add_i32 s73, 0, 0x1c000
	v_add_u32_e32 v118, s72, v214
	v_add_u32_e32 v178, s73, v214
	ds_read_b128 v[106:109], v118
	ds_read_b128 v[110:113], v118 offset:1024
	ds_read_b128 v[114:117], v118 offset:2048
	ds_read_b128 v[118:121], v118 offset:3072
	ds_read_b128 v[122:125], v178
	ds_read_b128 v[126:129], v178 offset:1024
	ds_read_b128 v[130:133], v178 offset:2048
	ds_read_b128 v[178:181], v178 offset:3072
	s_add_u32 s52, s52, 0x80000
	s_addc_u32 s53, s53, 0
	s_mov_b32 m0, s60
	ds_read_b128 v[182:185], v217 offset:32768
	ds_read_b128 v[186:189], v217 offset:33792
	ds_read_b128 v[190:193], v217 offset:34816
	ds_read_b128 v[218:221], v217 offset:35840
	ds_read_b128 v[222:225], v217 offset:36864
	ds_read_b128 v[226:229], v217 offset:37888
	ds_read_b128 v[230:233], v217 offset:38912
	global_load_lds_dwordx4 v172, s[52:53]
	s_mov_b32 m0, s61
	ds_read_b128 v[234:237], v217 offset:39936
	global_load_lds_dwordx4 v170, s[52:53]
	s_waitcnt vmcnt(8)
	s_waitcnt lgkmcnt(0)
	s_barrier
	s_waitcnt lgkmcnt(0)
	v_mfma_f32_16x16x32_bf16 v[154:157], v[106:109], v[182:185], v[154:157]
	v_mfma_f32_16x16x32_bf16 v[62:65], v[114:117], v[182:185], v[62:65]
	v_mfma_f32_16x16x32_bf16 v[150:153], v[106:109], v[190:193], v[150:153]
	v_mfma_f32_16x16x32_bf16 v[54:57], v[114:117], v[190:193], v[54:57]
	v_mfma_f32_16x16x32_bf16 v[142:145], v[106:109], v[222:225], v[142:145]
	v_mfma_f32_16x16x32_bf16 v[46:49], v[114:117], v[222:225], v[46:49]
	v_mfma_f32_16x16x32_bf16 v[102:105], v[106:109], v[230:233], v[102:105]
	v_mfma_f32_16x16x32_bf16 v[38:41], v[114:117], v[230:233], v[38:41]
	v_mfma_f32_16x16x32_bf16 v[154:157], v[110:113], v[186:189], v[154:157]
	v_mfma_f32_16x16x32_bf16 v[62:65], v[118:121], v[186:189], v[62:65]
	v_mfma_f32_16x16x32_bf16 v[150:153], v[110:113], v[218:221], v[150:153]
	v_mfma_f32_16x16x32_bf16 v[54:57], v[118:121], v[218:221], v[54:57]
	v_mfma_f32_16x16x32_bf16 v[142:145], v[110:113], v[226:229], v[142:145]
	v_mfma_f32_16x16x32_bf16 v[46:49], v[118:121], v[226:229], v[46:49]
	v_mfma_f32_16x16x32_bf16 v[102:105], v[110:113], v[234:237], v[102:105]
	v_mfma_f32_16x16x32_bf16 v[38:41], v[118:121], v[234:237], v[38:41]
	v_mfma_f32_16x16x32_bf16 v[134:137], v[122:125], v[182:185], v[134:137]
	v_mfma_f32_16x16x32_bf16 v[58:61], v[130:133], v[182:185], v[58:61]
	v_mfma_f32_16x16x32_bf16 v[146:149], v[122:125], v[190:193], v[146:149]
	v_mfma_f32_16x16x32_bf16 v[50:53], v[130:133], v[190:193], v[50:53]
	v_mfma_f32_16x16x32_bf16 v[138:141], v[122:125], v[222:225], v[138:141]
	v_mfma_f32_16x16x32_bf16 v[42:45], v[130:133], v[222:225], v[42:45]
	v_mfma_f32_16x16x32_bf16 v[98:101], v[122:125], v[230:233], v[98:101]
	v_mfma_f32_16x16x32_bf16 v[34:37], v[130:133], v[230:233], v[34:37]
	v_mfma_f32_16x16x32_bf16 v[134:137], v[126:129], v[186:189], v[134:137]
	v_mfma_f32_16x16x32_bf16 v[58:61], v[178:181], v[186:189], v[58:61]
	v_mfma_f32_16x16x32_bf16 v[146:149], v[126:129], v[218:221], v[146:149]
	v_mfma_f32_16x16x32_bf16 v[50:53], v[178:181], v[218:221], v[50:53]
	v_mfma_f32_16x16x32_bf16 v[138:141], v[126:129], v[226:229], v[138:141]
	v_mfma_f32_16x16x32_bf16 v[42:45], v[178:181], v[226:229], v[42:45]
	v_mfma_f32_16x16x32_bf16 v[98:101], v[126:129], v[234:237], v[98:101]
	v_mfma_f32_16x16x32_bf16 v[34:37], v[178:181], v[234:237], v[34:37]
	s_barrier
	s_add_i32 s52, s72, s57
	s_mov_b32 m0, s52
	ds_read_b128 v[182:185], v217 offset:49152
	ds_read_b128 v[186:189], v217 offset:50176
	ds_read_b128 v[190:193], v217 offset:51200
	ds_read_b128 v[218:221], v217 offset:52224
	global_load_lds_dwordx4 v0, vcc
	s_add_i32 m0, s52, 0x2000
	s_add_u32 s50, s50, 0x80080
	s_addc_u32 s51, s51, 0
	s_add_i32 s52, s73, s57
	global_load_lds_dwordx4 v168, vcc
	s_mov_b32 m0, s52
	ds_read_b128 v[222:225], v217 offset:53248
	global_load_lds_dwordx4 v0, s[50:51]
	s_add_i32 m0, s52, 0x2000
	ds_read_b128 v[226:229], v217 offset:54272
	global_load_lds_dwordx4 v168, s[50:51]
	s_mov_b32 m0, s62
	ds_read_b128 v[230:233], v217 offset:55296
	global_load_lds_dwordx4 v172, s[98:99]
	s_mov_b32 m0, s63
	ds_read_b128 v[234:237], v217 offset:56320
	global_load_lds_dwordx4 v170, s[98:99]
	s_waitcnt vmcnt(8)
	s_waitcnt lgkmcnt(0)
	s_barrier
	s_waitcnt lgkmcnt(0)
	v_mfma_f32_16x16x32_bf16 v[94:97], v[106:109], v[182:185], v[94:97]
	v_mfma_f32_16x16x32_bf16 v[30:33], v[114:117], v[182:185], v[30:33]
	v_mfma_f32_16x16x32_bf16 v[86:89], v[106:109], v[190:193], v[86:89]
	v_mfma_f32_16x16x32_bf16 v[22:25], v[114:117], v[190:193], v[22:25]
	v_mfma_f32_16x16x32_bf16 v[78:81], v[106:109], v[222:225], v[78:81]
	v_mfma_f32_16x16x32_bf16 v[14:17], v[114:117], v[222:225], v[14:17]
	v_mfma_f32_16x16x32_bf16 v[70:73], v[106:109], v[230:233], v[70:73]
	v_mfma_f32_16x16x32_bf16 v[6:9], v[114:117], v[230:233], v[6:9]
	v_mfma_f32_16x16x32_bf16 v[94:97], v[110:113], v[186:189], v[94:97]
	v_mfma_f32_16x16x32_bf16 v[30:33], v[118:121], v[186:189], v[30:33]
	v_mfma_f32_16x16x32_bf16 v[86:89], v[110:113], v[218:221], v[86:89]
	v_mfma_f32_16x16x32_bf16 v[22:25], v[118:121], v[218:221], v[22:25]
	v_mfma_f32_16x16x32_bf16 v[78:81], v[110:113], v[226:229], v[78:81]
	v_mfma_f32_16x16x32_bf16 v[14:17], v[118:121], v[226:229], v[14:17]
	v_mfma_f32_16x16x32_bf16 v[70:73], v[110:113], v[234:237], v[70:73]
	v_mfma_f32_16x16x32_bf16 v[6:9], v[118:121], v[234:237], v[6:9]
	v_mfma_f32_16x16x32_bf16 v[90:93], v[122:125], v[182:185], v[90:93]
	v_mfma_f32_16x16x32_bf16 v[26:29], v[130:133], v[182:185], v[26:29]
	v_mfma_f32_16x16x32_bf16 v[82:85], v[122:125], v[190:193], v[82:85]
	v_mfma_f32_16x16x32_bf16 v[18:21], v[130:133], v[190:193], v[18:21]
	v_mfma_f32_16x16x32_bf16 v[74:77], v[122:125], v[222:225], v[74:77]
	v_mfma_f32_16x16x32_bf16 v[10:13], v[130:133], v[222:225], v[10:13]
	v_mfma_f32_16x16x32_bf16 v[66:69], v[122:125], v[230:233], v[66:69]
	v_mfma_f32_16x16x32_bf16 v[2:5], v[130:133], v[230:233], v[2:5]
	v_mfma_f32_16x16x32_bf16 v[90:93], v[126:129], v[186:189], v[90:93]
	v_mfma_f32_16x16x32_bf16 v[26:29], v[178:181], v[186:189], v[26:29]
	v_mfma_f32_16x16x32_bf16 v[82:85], v[126:129], v[218:221], v[82:85]
	v_mfma_f32_16x16x32_bf16 v[18:21], v[178:181], v[218:221], v[18:21]
	v_mfma_f32_16x16x32_bf16 v[74:77], v[126:129], v[226:229], v[74:77]
	v_mfma_f32_16x16x32_bf16 v[10:13], v[178:181], v[226:229], v[10:13]
	v_mfma_f32_16x16x32_bf16 v[66:69], v[126:129], v[234:237], v[66:69]
	v_mfma_f32_16x16x32_bf16 v[2:5], v[178:181], v[234:237], v[2:5]
	s_barrier
	s_add_i32 s71, s71, 2
	s_add_u32 s48, s48, 0x100
	s_addc_u32 s49, s49, 0
	s_add_u32 s69, s69, 0x100
	s_addc_u32 s70, s70, 0
	s_cmp_gt_u32 s71, 29
	s_cbranch_scc0 .LBB0_43
	s_and_b64 vcc, exec, s[24:25]
	s_cbranch_vccz .LBB0_46
	s_barrier

; #define PG8_STAGE(bufoff, gbase, voff) do { _Pragma("unroll") for (int _i = 0; _i < 2; ++_i) \
;         __builtin_amdgcn_global_load_lds((const unsigned*)((const char*)(gbase) + (voff)[_i]), (PG8_LAS unsigned*)(lds + (bufoff) + ldsw + _i * 8192), 16, 0, 0); } while (0)
; #define PG8_LDA(dst, b, h) do { _Pragma("unroll") for (int m = 0; m < 4; ++m) _Pragma("unroll") for (int k = 0; k < 2; ++k) dst[m][k] = *(const PG8_LAS bf16x8*)(lds + PG8_SA(b, h) + aoff + m * 2048 + k * 1024); } while (0)
; #define PG8_LDB(dst, b, h) do { _Pragma("unroll") for (int n = 0; n < 2; ++n) _Pragma("unroll") for (int k = 0; k < 2; ++k) dst[n][k] = *(const PG8_LAS bf16x8*)(lds + PG8_SB(b, h) + boff + n * 2048 + k * 1024); } while (0)
; #define PG8_SCHED __builtin_amdgcn_sched_barrier(0)
; template <class Epi, class Sched, bool ALIGN_EPI = false, bool SP2 = false>
; __device__ __forceinline__ void gemm_phase(PG8_LAS unsigned char* lds, const Gemm g, const Sched& S, const Epi& E, int wave_in) {
;     ...
;             const bool last = (t == nt - 2);
;             const char* a1 = cA + (size_t)(t + 1) * kstep;
;             const char* a2 = last ? nA : cA + (size_t)(t + 2) * kstep; const char* b2 = last ? nB : cB + (size_t)(t + 2) * kstep;
;             const char* a3 = a2 + kstep; const char* b3 = b2 + kstep;
;             if (last && has_next) S.a_ready(nxt);
;             if constexpr (SP2) {
;             PG8_LDB(B0, 0, 0); PG8_LDB(B1, 0, 1); PG8_SCHED; PG8_LDA(At, 0, 0); PG8_STAGE(PG8_SA(1, 1), a1 + hstepA, voffA);
;     ...
; #pragma unroll
;         for (int a = 0; a < 2; ++a)
; #pragma unroll
;             for (int b = 0; b < 2; ++b)
; #pragma unroll
;                 for (int m = 0; m < 4; ++m)
; #pragma unroll
;                     for (int n = 0; n < 2; ++n) acc[a][b][m][n] = (f32x4){0.f, 0.f, 0.f, 0.f};
;         cur = nxt; cA = nA; cB = nB; ++ui;
.LBB0_83:
	s_ashr_i32 s17, s16, 31
	s_lshl_b64 s[18:19], s[16:17], 20
	v_readlane_b32 s20, v253, 62
	v_readlane_b32 s21, v253, 63
	s_add_u32 s18, s20, s18
	s_addc_u32 s19, s21, s19
	s_and_b64 s[20:21], s[4:5], exec
	s_cselect_b32 s17, s19, s23
	s_cselect_b32 s42, s18, s22
	s_ashr_i32 s11, s10, 31
	s_lshl_b64 s[20:21], s[10:11], 19
	s_add_u32 s20, s28, s20
	s_addc_u32 s21, s29, s21
	s_and_b64 s[26:27], s[4:5], exec
	s_cselect_b32 s11, s21, s25
	s_cselect_b32 s43, s20, s24
	s_add_u32 s22, s22, 0x80080
	s_addc_u32 s23, s23, 0
	s_add_u32 s44, s24, 0x100
	v_mov_b32_e32 v2, 0
	s_addc_u32 s45, s25, 0
	s_mov_b32 s46, -2
	v_mov_b32_e32 v3, v2
	v_mov_b32_e32 v4, v2
	v_mov_b32_e32 v5, v2
	v_mov_b32_e32 v6, v2
	v_mov_b32_e32 v7, v2
	v_mov_b32_e32 v8, v2
	v_mov_b32_e32 v9, v2
	v_mov_b32_e32 v14, v2
	v_mov_b32_e32 v15, v2
	v_mov_b32_e32 v16, v2
	v_mov_b32_e32 v17, v2
	v_mov_b32_e32 v18, v2
	v_mov_b32_e32 v19, v2
	s_waitcnt vmcnt(0)
	v_mov_b32_e32 v20, v2
	v_mov_b32_e32 v21, v2
	v_mov_b32_e32 v30, v2
	v_mov_b32_e32 v31, v2
	v_mov_b32_e32 v32, v2
	v_mov_b32_e32 v33, v2
	v_mov_b32_e32 v34, v2
	v_mov_b32_e32 v35, v2
	v_mov_b32_e32 v36, v2
	v_mov_b32_e32 v37, v2
	v_mov_b32_e32 v46, v2
	v_mov_b32_e32 v47, v2
	v_mov_b32_e32 v48, v2
	v_mov_b32_e32 v49, v2
	v_mov_b32_e32 v50, v2
	v_mov_b32_e32 v51, v2
	v_mov_b32_e32 v52, v2
	v_mov_b32_e32 v53, v2
	v_mov_b32_e32 v10, v2
	v_mov_b32_e32 v11, v2
	v_mov_b32_e32 v12, v2
	v_mov_b32_e32 v13, v2
	v_mov_b32_e32 v22, v2
	v_mov_b32_e32 v23, v2
	v_mov_b32_e32 v24, v2
	v_mov_b32_e32 v25, v2
	v_mov_b32_e32 v26, v2
	v_mov_b32_e32 v27, v2
	v_mov_b32_e32 v28, v2
	v_mov_b32_e32 v29, v2
	v_mov_b32_e32 v38, v2
	v_mov_b32_e32 v39, v2
	v_mov_b32_e32 v40, v2
	v_mov_b32_e32 v41, v2
	v_mov_b32_e32 v42, v2
	v_mov_b32_e32 v43, v2
	v_mov_b32_e32 v44, v2
	v_mov_b32_e32 v45, v2
	v_mov_b32_e32 v54, v2
	v_mov_b32_e32 v55, v2
	v_mov_b32_e32 v56, v2
	v_mov_b32_e32 v57, v2
	v_mov_b32_e32 v58, v2
	v_mov_b32_e32 v59, v2
	v_mov_b32_e32 v60, v2
	v_mov_b32_e32 v61, v2
	v_mov_b32_e32 v62, v2
	v_mov_b32_e32 v63, v2
	v_mov_b32_e32 v64, v2
	v_mov_b32_e32 v65, v2
	v_mov_b32_e32 v66, v2
	v_mov_b32_e32 v67, v2
	v_mov_b32_e32 v68, v2
	v_mov_b32_e32 v69, v2
	v_mov_b32_e32 v70, v2
	v_mov_b32_e32 v71, v2
	v_mov_b32_e32 v72, v2
	v_mov_b32_e32 v73, v2
	v_mov_b32_e32 v78, v2
	v_mov_b32_e32 v79, v2
	v_mov_b32_e32 v80, v2
	v_mov_b32_e32 v81, v2
	v_mov_b32_e32 v82, v2
	v_mov_b32_e32 v83, v2
	v_mov_b32_e32 v84, v2
	v_mov_b32_e32 v85, v2
	v_mov_b32_e32 v94, v2
	v_mov_b32_e32 v95, v2
	v_mov_b32_e32 v96, v2
	v_mov_b32_e32 v97, v2
	v_mov_b32_e32 v98, v2
	v_mov_b32_e32 v99, v2
	v_mov_b32_e32 v100, v2
	v_mov_b32_e32 v101, v2
	v_mov_b32_e32 v110, v2
	v_mov_b32_e32 v111, v2
	v_mov_b32_e32 v112, v2
	v_mov_b32_e32 v113, v2
	v_mov_b32_e32 v114, v2
	v_mov_b32_e32 v115, v2
	v_mov_b32_e32 v116, v2
	v_mov_b32_e32 v117, v2
	v_mov_b32_e32 v74, v2
	v_mov_b32_e32 v75, v2
	v_mov_b32_e32 v76, v2
	v_mov_b32_e32 v77, v2
	v_mov_b32_e32 v86, v2
	v_mov_b32_e32 v87, v2
	v_mov_b32_e32 v88, v2
	v_mov_b32_e32 v89, v2
	v_mov_b32_e32 v90, v2
	v_mov_b32_e32 v91, v2
	v_mov_b32_e32 v92, v2
	v_mov_b32_e32 v93, v2
	v_mov_b32_e32 v102, v2
	v_mov_b32_e32 v103, v2
	v_mov_b32_e32 v104, v2
	v_mov_b32_e32 v105, v2
	v_mov_b32_e32 v106, v2
	v_mov_b32_e32 v107, v2
	v_mov_b32_e32 v108, v2
	v_mov_b32_e32 v109, v2
	v_mov_b32_e32 v118, v2
	v_mov_b32_e32 v119, v2
	v_mov_b32_e32 v120, v2
	v_mov_b32_e32 v121, v2
	v_mov_b32_e32 v122, v2
	v_mov_b32_e32 v123, v2
	v_mov_b32_e32 v124, v2
	v_mov_b32_e32 v125, v2
	v_mov_b32_e32 v126, v2
	v_mov_b32_e32 v127, v2
	v_mov_b32_e32 v128, v2
	v_mov_b32_e32 v129, v2
	s_nop 0
	s_nop 0
	s_nop 0
.LBB0_84:
	s_add_u32 s24, s22, 0xfff80080
	s_addc_u32 s25, s23, -1
	s_add_i32 s47, 0, 0x10000
	s_cmp_eq_u32 s46, 12
	s_cselect_b32 s27, s17, s25
	s_cselect_b32 s26, s42, s24
	v_add_u32_e32 v144, s47, v147
	s_cselect_b32 s25, s11, s45
	s_cselect_b32 s24, s43, s44
	s_add_i32 s50, 0, 0x14000
	ds_read_b128 v[140:143], v144
	ds_read_b128 v[150:153], v144 offset:1024
	ds_read_b128 v[154:157], v144 offset:2048
	ds_read_b128 v[168:171], v144 offset:3072
	v_add_u32_e32 v144, s50, v147
	ds_read_b128 v[172:175], v144
	ds_read_b128 v[176:179], v144 offset:1024
	ds_read_b128 v[180:183], v144 offset:2048
	ds_read_b128 v[184:187], v144 offset:3072
	v_lshl_add_u64 v[144:145], s[22:23], 0, v[136:137]
	s_add_i32 m0, s31, 0xc000
	ds_read_b128 v[188:191], v149
	ds_read_b128 v[212:215], v149 offset:1024
	ds_read_b128 v[216:219], v149 offset:2048
	ds_read_b128 v[220:223], v149 offset:3072
	ds_read_b128 v[224:227], v149 offset:4096
	ds_read_b128 v[228:231], v149 offset:5120
	ds_read_b128 v[232:235], v149 offset:6144
	ds_read_b128 v[236:239], v149 offset:7168
	global_load_lds_dwordx4 v[144:145], off
	v_lshl_add_u64 v[144:145], s[22:23], 0, v[138:139]
	s_add_i32 m0, s31, 0xe000
	s_nop 0
	global_load_lds_dwordx4 v[144:145], off
	s_waitcnt vmcnt(8)
	s_waitcnt lgkmcnt(0)
	s_barrier
; #define PG8_STAGE(bufoff, gbase, voff) do { _Pragma("unroll") for (int _i = 0; _i < 2; ++_i) \
;         __builtin_amdgcn_global_load_lds((const unsigned*)((const char*)(gbase) + (voff)[_i]), (PG8_LAS unsigned*)(lds + (bufoff) + ldsw + _i * 8192), 16, 0, 0); } while (0)
; #define PG8_LDA(dst, b, h) do { _Pragma("unroll") for (int m = 0; m < 4; ++m) _Pragma("unroll") for (int k = 0; k < 2; ++k) dst[m][k] = *(const PG8_LAS bf16x8*)(lds + PG8_SA(b, h) + aoff + m * 2048 + k * 1024); } while (0)
; #define PG8_MMA(ai, bj, At, Bt) do { __builtin_amdgcn_s_setprio(1); _Pragma("unroll") for (int m = 0; m < 4; ++m) _Pragma("unroll") for (int n = 0; n < 2; ++n) _Pragma("unroll") for (int k = 0; k < 2; ++k) \
;         acc[ai][bj][m][n] = __builtin_amdgcn_mfma_f32_16x16x32_bf16(Bt[n][k], At[m][k], acc[ai][bj][m][n], 0, 0, 0); __builtin_amdgcn_s_setprio(0); } while (0)
; #define PG8_WAIT_V(n) asm volatile("s_waitcnt vmcnt(" #n ")" ::: "memory")
; #define PG8_WAIT_L(n) asm volatile("s_waitcnt lgkmcnt(" #n ")" ::: "memory")
; #define PG8_BAR __builtin_amdgcn_s_barrier()
; #define PG8_SCHED __builtin_amdgcn_sched_barrier(0)
; template <class Epi, class Sched, bool ALIGN_EPI = false, bool SP2 = false>
; __device__ __forceinline__ void gemm_phase(PG8_LAS unsigned char* lds, const Gemm g, const Sched& S, const Epi& E, int wave_in) {
;     ...
;             PG8_WAIT_V(8); PG8_WAIT_L(0); PG8_BAR; PG8_MMA(0, 0, At, B0); PG8_MMA(0, 1, At, B1); PG8_BAR; PG8_SCHED;
;             PG8_LDA(At, 0, 1); PG8_STAGE(PG8_SB(0, 0), b2, voffB); PG8_STAGE(PG8_SB(0, 1), b2 + hstep, voffB); PG8_STAGE(PG8_SA(0, 0), a2, voffA);
;             PG8_WAIT_V(8); PG8_WAIT_L(0); PG8_BAR; PG8_MMA(1, 0, At, B0); PG8_MMA(1, 1, At, B1); PG8_BAR; PG8_SCHED;
	s_waitcnt lgkmcnt(0)
	v_mfma_f32_16x16x32_bf16 v[126:129], v[140:143], v[188:191], v[126:129]
	v_mfma_f32_16x16x32_bf16 v[122:125], v[154:157], v[188:191], v[122:125]
	v_mfma_f32_16x16x32_bf16 v[118:121], v[140:143], v[216:219], v[118:121]
	v_mfma_f32_16x16x32_bf16 v[106:109], v[154:157], v[216:219], v[106:109]
	v_mfma_f32_16x16x32_bf16 v[102:105], v[140:143], v[224:227], v[102:105]
	v_mfma_f32_16x16x32_bf16 v[90:93], v[154:157], v[224:227], v[90:93]
	v_mfma_f32_16x16x32_bf16 v[86:89], v[140:143], v[232:235], v[86:89]
	v_mfma_f32_16x16x32_bf16 v[74:77], v[154:157], v[232:235], v[74:77]
	v_mfma_f32_16x16x32_bf16 v[126:129], v[150:153], v[212:215], v[126:129]
	v_mfma_f32_16x16x32_bf16 v[122:125], v[168:171], v[212:215], v[122:125]
	v_mfma_f32_16x16x32_bf16 v[118:121], v[150:153], v[220:223], v[118:121]
	v_mfma_f32_16x16x32_bf16 v[106:109], v[168:171], v[220:223], v[106:109]
	v_mfma_f32_16x16x32_bf16 v[102:105], v[150:153], v[228:231], v[102:105]
	v_mfma_f32_16x16x32_bf16 v[90:93], v[168:171], v[228:231], v[90:93]
	v_mfma_f32_16x16x32_bf16 v[86:89], v[150:153], v[236:239], v[86:89]
	v_mfma_f32_16x16x32_bf16 v[74:77], v[168:171], v[236:239], v[74:77]
	v_mfma_f32_16x16x32_bf16 v[114:117], v[172:175], v[188:191], v[114:117]
	v_mfma_f32_16x16x32_bf16 v[110:113], v[180:183], v[188:191], v[110:113]
	v_mfma_f32_16x16x32_bf16 v[98:101], v[172:175], v[216:219], v[98:101]
	v_mfma_f32_16x16x32_bf16 v[94:97], v[180:183], v[216:219], v[94:97]
	v_mfma_f32_16x16x32_bf16 v[82:85], v[172:175], v[224:227], v[82:85]
	v_mfma_f32_16x16x32_bf16 v[78:81], v[180:183], v[224:227], v[78:81]
	v_mfma_f32_16x16x32_bf16 v[70:73], v[172:175], v[232:235], v[70:73]
	v_mfma_f32_16x16x32_bf16 v[66:69], v[180:183], v[232:235], v[66:69]
	v_mfma_f32_16x16x32_bf16 v[114:117], v[176:179], v[212:215], v[114:117]
	v_mfma_f32_16x16x32_bf16 v[110:113], v[184:187], v[212:215], v[110:113]
	v_mfma_f32_16x16x32_bf16 v[98:101], v[176:179], v[220:223], v[98:101]
	v_mfma_f32_16x16x32_bf16 v[94:97], v[184:187], v[220:223], v[94:97]
	v_mfma_f32_16x16x32_bf16 v[82:85], v[176:179], v[228:231], v[82:85]
	v_mfma_f32_16x16x32_bf16 v[78:81], v[184:187], v[228:231], v[78:81]
	v_mfma_f32_16x16x32_bf16 v[70:73], v[176:179], v[236:239], v[70:73]
	v_mfma_f32_16x16x32_bf16 v[66:69], v[184:187], v[236:239], v[66:69]
	s_barrier
	s_add_i32 s47, s47, s30
	v_lshl_add_u64 v[144:145], s[24:25], 0, v[0:1]
	s_mov_b32 m0, s47
	ds_read_b128 v[188:191], v149 offset:16384
	ds_read_b128 v[212:215], v149 offset:17408
	ds_read_b128 v[216:219], v149 offset:18432
	ds_read_b128 v[220:223], v149 offset:19456
	ds_read_b128 v[224:227], v149 offset:20480
	ds_read_b128 v[228:231], v149 offset:21504
	ds_read_b128 v[232:235], v149 offset:22528
	ds_read_b128 v[236:239], v149 offset:23552
	global_load_lds_dwordx4 v[144:145], off
	s_add_i32 m0, s47, 0x2000
	s_add_u32 s48, s24, 0x40000
	v_lshl_add_u64 v[192:193], s[24:25], 0, v[130:131]
	s_addc_u32 s49, s25, 0
	s_add_i32 s47, s50, s30
	global_load_lds_dwordx4 v[192:193], off
	v_lshl_add_u64 v[240:241], s[48:49], 0, v[0:1]
	s_mov_b32 m0, s47
	v_lshl_add_u64 v[242:243], s[26:27], 0, v[132:133]
	global_load_lds_dwordx4 v[240:241], off
	v_lshl_add_u64 v[240:241], s[48:49], 0, v[130:131]
	s_add_i32 m0, s47, 0x2000
	s_nop 0
	global_load_lds_dwordx4 v[240:241], off
	v_lshl_add_u64 v[240:241], s[26:27], 0, v[134:135]
	s_mov_b32 m0, s31
	s_nop 0
	global_load_lds_dwordx4 v[240:241], off
	s_mov_b32 m0, s34
	s_nop 0
	global_load_lds_dwordx4 v[242:243], off
	s_waitcnt vmcnt(8)
	s_waitcnt lgkmcnt(0)
	s_barrier
	s_waitcnt lgkmcnt(0)
	v_mfma_f32_16x16x32_bf16 v[62:65], v[140:143], v[188:191], v[62:65]
	v_mfma_f32_16x16x32_bf16 v[58:61], v[154:157], v[188:191], v[58:61]
	v_mfma_f32_16x16x32_bf16 v[54:57], v[140:143], v[216:219], v[54:57]
	v_mfma_f32_16x16x32_bf16 v[42:45], v[154:157], v[216:219], v[42:45]
	v_mfma_f32_16x16x32_bf16 v[38:41], v[140:143], v[224:227], v[38:41]
	v_mfma_f32_16x16x32_bf16 v[26:29], v[154:157], v[224:227], v[26:29]
	v_mfma_f32_16x16x32_bf16 v[22:25], v[140:143], v[232:235], v[22:25]
	v_mfma_f32_16x16x32_bf16 v[10:13], v[154:157], v[232:235], v[10:13]
	v_mfma_f32_16x16x32_bf16 v[62:65], v[150:153], v[212:215], v[62:65]
	v_mfma_f32_16x16x32_bf16 v[58:61], v[168:171], v[212:215], v[58:61]
	v_mfma_f32_16x16x32_bf16 v[54:57], v[150:153], v[220:223], v[54:57]
	v_mfma_f32_16x16x32_bf16 v[42:45], v[168:171], v[220:223], v[42:45]
	v_mfma_f32_16x16x32_bf16 v[38:41], v[150:153], v[228:231], v[38:41]
	v_mfma_f32_16x16x32_bf16 v[26:29], v[168:171], v[228:231], v[26:29]
	v_mfma_f32_16x16x32_bf16 v[22:25], v[150:153], v[236:239], v[22:25]
	v_mfma_f32_16x16x32_bf16 v[10:13], v[168:171], v[236:239], v[10:13]
	v_mfma_f32_16x16x32_bf16 v[50:53], v[172:175], v[188:191], v[50:53]
	v_mfma_f32_16x16x32_bf16 v[46:49], v[180:183], v[188:191], v[46:49]
	v_mfma_f32_16x16x32_bf16 v[34:37], v[172:175], v[216:219], v[34:37]
	v_mfma_f32_16x16x32_bf16 v[30:33], v[180:183], v[216:219], v[30:33]
	v_mfma_f32_16x16x32_bf16 v[18:21], v[172:175], v[224:227], v[18:21]
	v_mfma_f32_16x16x32_bf16 v[14:17], v[180:183], v[224:227], v[14:17]
	v_mfma_f32_16x16x32_bf16 v[6:9], v[172:175], v[232:235], v[6:9]
	v_mfma_f32_16x16x32_bf16 v[2:5], v[180:183], v[232:235], v[2:5]
	v_mfma_f32_16x16x32_bf16 v[50:53], v[176:179], v[212:215], v[50:53]
	v_mfma_f32_16x16x32_bf16 v[46:49], v[184:187], v[212:215], v[46:49]
	v_mfma_f32_16x16x32_bf16 v[34:37], v[176:179], v[220:223], v[34:37]
	v_mfma_f32_16x16x32_bf16 v[30:33], v[184:187], v[220:223], v[30:33]
	v_mfma_f32_16x16x32_bf16 v[18:21], v[176:179], v[228:231], v[18:21]
	v_mfma_f32_16x16x32_bf16 v[14:17], v[184:187], v[228:231], v[14:17]
	v_mfma_f32_16x16x32_bf16 v[6:9], v[176:179], v[236:239], v[6:9]
	v_mfma_f32_16x16x32_bf16 v[2:5], v[184:187], v[236:239], v[2:5]
	s_barrier
; #define PG8_STAGE(bufoff, gbase, voff) do { _Pragma("unroll") for (int _i = 0; _i < 2; ++_i) \
;         __builtin_amdgcn_global_load_lds((const unsigned*)((const char*)(gbase) + (voff)[_i]), (PG8_LAS unsigned*)(lds + (bufoff) + ldsw + _i * 8192), 16, 0, 0); } while (0)
; #define PG8_LDA(dst, b, h) do { _Pragma("unroll") for (int m = 0; m < 4; ++m) _Pragma("unroll") for (int k = 0; k < 2; ++k) dst[m][k] = *(const PG8_LAS bf16x8*)(lds + PG8_SA(b, h) + aoff + m * 2048 + k * 1024); } while (0)
; #define PG8_LDB(dst, b, h) do { _Pragma("unroll") for (int n = 0; n < 2; ++n) _Pragma("unroll") for (int k = 0; k < 2; ++k) dst[n][k] = *(const PG8_LAS bf16x8*)(lds + PG8_SB(b, h) + boff + n * 2048 + k * 1024); } while (0)
; #define PG8_MMA(ai, bj, At, Bt) do { __builtin_amdgcn_s_setprio(1); _Pragma("unroll") for (int m = 0; m < 4; ++m) _Pragma("unroll") for (int n = 0; n < 2; ++n) _Pragma("unroll") for (int k = 0; k < 2; ++k) \
;         acc[ai][bj][m][n] = __builtin_amdgcn_mfma_f32_16x16x32_bf16(Bt[n][k], At[m][k], acc[ai][bj][m][n], 0, 0, 0); __builtin_amdgcn_s_setprio(0); } while (0)
; #define PG8_WAIT_V(n) asm volatile("s_waitcnt vmcnt(" #n ")" ::: "memory")
; #define PG8_WAIT_L(n) asm volatile("s_waitcnt lgkmcnt(" #n ")" ::: "memory")
; #define PG8_BAR __builtin_amdgcn_s_barrier()
; #define PG8_SCHED __builtin_amdgcn_sched_barrier(0)
; template <class Epi, class Sched, bool ALIGN_EPI = false, bool SP2 = false>
; __device__ __forceinline__ void gemm_phase(PG8_LAS unsigned char* lds, const Gemm g, const Sched& S, const Epi& E, int wave_in) {
;     ...
;             PG8_LDB(B0, 1, 0); PG8_LDB(B1, 1, 1); PG8_SCHED; PG8_LDA(At, 1, 0); PG8_STAGE(PG8_SA(0, 1), a2 + hstepA, voffA);
;             PG8_WAIT_V(8); PG8_WAIT_L(0); PG8_BAR; PG8_MMA(0, 0, At, B0); PG8_MMA(0, 1, At, B1); PG8_BAR; PG8_SCHED;
	s_add_i32 s47, 0, 0x18000
	s_add_i32 s48, 0, 0x1c000
	v_add_u32_e32 v168, s47, v147
	v_add_u32_e32 v184, s48, v147
	ds_read_b128 v[140:143], v168
	ds_read_b128 v[150:153], v168 offset:1024
	ds_read_b128 v[154:157], v168 offset:2048
	ds_read_b128 v[168:171], v168 offset:3072
	ds_read_b128 v[172:175], v184
	ds_read_b128 v[176:179], v184 offset:1024
	ds_read_b128 v[180:183], v184 offset:2048
	ds_read_b128 v[184:187], v184 offset:3072
	s_add_u32 s26, s26, 0x80000
	s_addc_u32 s27, s27, 0
	s_mov_b32 m0, s35
	v_lshl_add_u64 v[244:245], s[26:27], 0, v[134:135]
	ds_read_b128 v[188:191], v149 offset:32768
	ds_read_b128 v[212:215], v149 offset:33792
	ds_read_b128 v[216:219], v149 offset:34816
	ds_read_b128 v[220:223], v149 offset:35840
	ds_read_b128 v[224:227], v149 offset:36864
	ds_read_b128 v[228:231], v149 offset:37888
	ds_read_b128 v[232:235], v149 offset:38912
	ds_read_b128 v[236:239], v149 offset:39936
	global_load_lds_dwordx4 v[244:245], off
	v_lshl_add_u64 v[244:245], s[26:27], 0, v[132:133]
	s_mov_b32 m0, s36
	s_nop 0
	global_load_lds_dwordx4 v[244:245], off
	s_waitcnt vmcnt(8)
	s_waitcnt lgkmcnt(0)
	s_barrier
	s_waitcnt lgkmcnt(0)
	v_mfma_f32_16x16x32_bf16 v[126:129], v[140:143], v[188:191], v[126:129]
	v_mfma_f32_16x16x32_bf16 v[122:125], v[154:157], v[188:191], v[122:125]
	v_mfma_f32_16x16x32_bf16 v[118:121], v[140:143], v[216:219], v[118:121]
	v_mfma_f32_16x16x32_bf16 v[106:109], v[154:157], v[216:219], v[106:109]
	v_mfma_f32_16x16x32_bf16 v[102:105], v[140:143], v[224:227], v[102:105]
	v_mfma_f32_16x16x32_bf16 v[90:93], v[154:157], v[224:227], v[90:93]
	v_mfma_f32_16x16x32_bf16 v[86:89], v[140:143], v[232:235], v[86:89]
	v_mfma_f32_16x16x32_bf16 v[74:77], v[154:157], v[232:235], v[74:77]
	v_mfma_f32_16x16x32_bf16 v[126:129], v[150:153], v[212:215], v[126:129]
	v_mfma_f32_16x16x32_bf16 v[122:125], v[168:171], v[212:215], v[122:125]
	v_mfma_f32_16x16x32_bf16 v[118:121], v[150:153], v[220:223], v[118:121]
	v_mfma_f32_16x16x32_bf16 v[106:109], v[168:171], v[220:223], v[106:109]
	v_mfma_f32_16x16x32_bf16 v[102:105], v[150:153], v[228:231], v[102:105]
	v_mfma_f32_16x16x32_bf16 v[90:93], v[168:171], v[228:231], v[90:93]
	v_mfma_f32_16x16x32_bf16 v[86:89], v[150:153], v[236:239], v[86:89]
	v_mfma_f32_16x16x32_bf16 v[74:77], v[168:171], v[236:239], v[74:77]
	v_mfma_f32_16x16x32_bf16 v[114:117], v[172:175], v[188:191], v[114:117]
	v_mfma_f32_16x16x32_bf16 v[110:113], v[180:183], v[188:191], v[110:113]
	v_mfma_f32_16x16x32_bf16 v[98:101], v[172:175], v[216:219], v[98:101]
	v_mfma_f32_16x16x32_bf16 v[94:97], v[180:183], v[216:219], v[94:97]
	v_mfma_f32_16x16x32_bf16 v[82:85], v[172:175], v[224:227], v[82:85]
	v_mfma_f32_16x16x32_bf16 v[78:81], v[180:183], v[224:227], v[78:81]
	v_mfma_f32_16x16x32_bf16 v[70:73], v[172:175], v[232:235], v[70:73]
	v_mfma_f32_16x16x32_bf16 v[66:69], v[180:183], v[232:235], v[66:69]
	v_mfma_f32_16x16x32_bf16 v[114:117], v[176:179], v[212:215], v[114:117]
	v_mfma_f32_16x16x32_bf16 v[110:113], v[184:187], v[212:215], v[110:113]
	v_mfma_f32_16x16x32_bf16 v[98:101], v[176:179], v[220:223], v[98:101]
	v_mfma_f32_16x16x32_bf16 v[94:97], v[184:187], v[220:223], v[94:97]
	v_mfma_f32_16x16x32_bf16 v[82:85], v[176:179], v[228:231], v[82:85]
	v_mfma_f32_16x16x32_bf16 v[78:81], v[184:187], v[228:231], v[78:81]
	v_mfma_f32_16x16x32_bf16 v[70:73], v[176:179], v[236:239], v[70:73]
	v_mfma_f32_16x16x32_bf16 v[66:69], v[184:187], v[236:239], v[66:69]
	s_barrier
; #define PG8_STAGE(bufoff, gbase, voff) do { _Pragma("unroll") for (int _i = 0; _i < 2; ++_i) \
;         __builtin_amdgcn_global_load_lds((const unsigned*)((const char*)(gbase) + (voff)[_i]), (PG8_LAS unsigned*)(lds + (bufoff) + ldsw + _i * 8192), 16, 0, 0); } while (0)
; #define PG8_LDA(dst, b, h) do { _Pragma("unroll") for (int m = 0; m < 4; ++m) _Pragma("unroll") for (int k = 0; k < 2; ++k) dst[m][k] = *(const PG8_LAS bf16x8*)(lds + PG8_SA(b, h) + aoff + m * 2048 + k * 1024); } while (0)
; #define PG8_MMA(ai, bj, At, Bt) do { __builtin_amdgcn_s_setprio(1); _Pragma("unroll") for (int m = 0; m < 4; ++m) _Pragma("unroll") for (int n = 0; n < 2; ++n) _Pragma("unroll") for (int k = 0; k < 2; ++k) \
;         acc[ai][bj][m][n] = __builtin_amdgcn_mfma_f32_16x16x32_bf16(Bt[n][k], At[m][k], acc[ai][bj][m][n], 0, 0, 0); __builtin_amdgcn_s_setprio(0); } while (0)
; #define PG8_WAIT_V(n) asm volatile("s_waitcnt vmcnt(" #n ")" ::: "memory")
; #define PG8_WAIT_L(n) asm volatile("s_waitcnt lgkmcnt(" #n ")" ::: "memory")
; #define PG8_BAR __builtin_amdgcn_s_barrier()
; #define PG8_SCHED __builtin_amdgcn_sched_barrier(0)
; template <class Epi, class Sched, bool ALIGN_EPI = false, bool SP2 = false>
; __device__ __forceinline__ void gemm_phase(PG8_LAS unsigned char* lds, const Gemm g, const Sched& S, const Epi& E, int wave_in) {
;     ...
;         for (int t = 0; t < nt; t += 2) {
;             const bool last = (t == nt - 2);
;             const char* a1 = cA + (size_t)(t + 1) * kstep;
;             const char* a2 = last ? nA : cA + (size_t)(t + 2) * kstep; const char* b2 = last ? nB : cB + (size_t)(t + 2) * kstep;
;             const char* a3 = a2 + kstep; const char* b3 = b2 + kstep;
;     ...
;             PG8_LDA(At, 1, 1); PG8_STAGE(PG8_SB(1, 0), b3, voffB); PG8_STAGE(PG8_SB(1, 1), b3 + hstep, voffB); PG8_STAGE(PG8_SA(1, 0), a3, voffA);
;             PG8_WAIT_V(8); PG8_WAIT_L(0); PG8_BAR; PG8_MMA(1, 0, At, B0); PG8_MMA(1, 1, At, B1); PG8_BAR; PG8_SCHED;
	s_add_i32 s26, s47, s30
	v_lshl_add_u64 v[144:145], v[144:145], 0, s[84:85]
	s_mov_b32 m0, s26
	ds_read_b128 v[188:191], v149 offset:49152
	ds_read_b128 v[212:215], v149 offset:50176
	ds_read_b128 v[216:219], v149 offset:51200
	ds_read_b128 v[220:223], v149 offset:52224
	ds_read_b128 v[224:227], v149 offset:53248
	ds_read_b128 v[228:231], v149 offset:54272
	ds_read_b128 v[232:235], v149 offset:55296
	ds_read_b128 v[236:239], v149 offset:56320
	global_load_lds_dwordx4 v[144:145], off
	s_add_i32 m0, s26, 0x2000
	s_add_u32 s24, s24, 0x40080
	v_lshl_add_u64 v[144:145], v[192:193], 0, s[84:85]
	s_addc_u32 s25, s25, 0
	s_add_i32 s26, s48, s30
	global_load_lds_dwordx4 v[144:145], off
	v_lshl_add_u64 v[144:145], s[24:25], 0, v[0:1]
	s_mov_b32 m0, s26
	s_nop 0
	global_load_lds_dwordx4 v[144:145], off
	v_lshl_add_u64 v[144:145], s[24:25], 0, v[130:131]
	s_add_i32 m0, s26, 0x2000
	s_nop 0
	global_load_lds_dwordx4 v[144:145], off
	v_lshl_add_u64 v[144:145], v[240:241], 0, s[84:85]
	s_mov_b32 m0, s37
	s_nop 0
	global_load_lds_dwordx4 v[144:145], off
	v_lshl_add_u64 v[144:145], v[242:243], 0, s[84:85]
	s_mov_b32 m0, s38
	s_nop 0
	global_load_lds_dwordx4 v[144:145], off
	s_waitcnt vmcnt(8)
	s_waitcnt lgkmcnt(0)
	s_barrier
	s_waitcnt lgkmcnt(0)
	v_mfma_f32_16x16x32_bf16 v[62:65], v[140:143], v[188:191], v[62:65]
	v_mfma_f32_16x16x32_bf16 v[58:61], v[154:157], v[188:191], v[58:61]
	v_mfma_f32_16x16x32_bf16 v[54:57], v[140:143], v[216:219], v[54:57]
	v_mfma_f32_16x16x32_bf16 v[42:45], v[154:157], v[216:219], v[42:45]
	v_mfma_f32_16x16x32_bf16 v[38:41], v[140:143], v[224:227], v[38:41]
	v_mfma_f32_16x16x32_bf16 v[26:29], v[154:157], v[224:227], v[26:29]
	v_mfma_f32_16x16x32_bf16 v[22:25], v[140:143], v[232:235], v[22:25]
	v_mfma_f32_16x16x32_bf16 v[10:13], v[154:157], v[232:235], v[10:13]
	v_mfma_f32_16x16x32_bf16 v[62:65], v[150:153], v[212:215], v[62:65]
	v_mfma_f32_16x16x32_bf16 v[58:61], v[168:171], v[212:215], v[58:61]
	v_mfma_f32_16x16x32_bf16 v[54:57], v[150:153], v[220:223], v[54:57]
	v_mfma_f32_16x16x32_bf16 v[42:45], v[168:171], v[220:223], v[42:45]
	v_mfma_f32_16x16x32_bf16 v[38:41], v[150:153], v[228:231], v[38:41]
	v_mfma_f32_16x16x32_bf16 v[26:29], v[168:171], v[228:231], v[26:29]
	v_mfma_f32_16x16x32_bf16 v[22:25], v[150:153], v[236:239], v[22:25]
	v_mfma_f32_16x16x32_bf16 v[10:13], v[168:171], v[236:239], v[10:13]
	v_mfma_f32_16x16x32_bf16 v[50:53], v[172:175], v[188:191], v[50:53]
	v_mfma_f32_16x16x32_bf16 v[46:49], v[180:183], v[188:191], v[46:49]
	v_mfma_f32_16x16x32_bf16 v[34:37], v[172:175], v[216:219], v[34:37]
	v_mfma_f32_16x16x32_bf16 v[30:33], v[180:183], v[216:219], v[30:33]
	v_mfma_f32_16x16x32_bf16 v[18:21], v[172:175], v[224:227], v[18:21]
	v_mfma_f32_16x16x32_bf16 v[14:17], v[180:183], v[224:227], v[14:17]
	v_mfma_f32_16x16x32_bf16 v[6:9], v[172:175], v[232:235], v[6:9]
	v_mfma_f32_16x16x32_bf16 v[2:5], v[180:183], v[232:235], v[2:5]
	v_mfma_f32_16x16x32_bf16 v[50:53], v[176:179], v[212:215], v[50:53]
	v_mfma_f32_16x16x32_bf16 v[46:49], v[184:187], v[212:215], v[46:49]
	v_mfma_f32_16x16x32_bf16 v[34:37], v[176:179], v[220:223], v[34:37]
	v_mfma_f32_16x16x32_bf16 v[30:33], v[184:187], v[220:223], v[30:33]
	v_mfma_f32_16x16x32_bf16 v[18:21], v[176:179], v[228:231], v[18:21]
	v_mfma_f32_16x16x32_bf16 v[14:17], v[184:187], v[228:231], v[14:17]
	v_mfma_f32_16x16x32_bf16 v[6:9], v[176:179], v[236:239], v[6:9]
	v_mfma_f32_16x16x32_bf16 v[2:5], v[184:187], v[236:239], v[2:5]
	s_barrier
	s_add_i32 s46, s46, 2
	s_add_u32 s22, s22, 0x100
	s_addc_u32 s23, s23, 0
	s_add_u32 s44, s44, 0x100
	s_addc_u32 s45, s45, 0
	s_cmp_gt_u32 s46, 13
	s_cbranch_scc0 .LBB0_84
	s_and_b64 vcc, exec, s[8:9]
	v_readlane_b32 s26, v254, 6
	v_readlane_b32 s27, v254, 7
	s_cbranch_vccz .LBB0_87
	s_barrier

; #define PG8_STAGE(bufoff, gbase, voff) do { _Pragma("unroll") for (int _i = 0; _i < 2; ++_i) \
;         __builtin_amdgcn_global_load_lds((const unsigned*)((const char*)(gbase) + (voff)[_i]), (PG8_LAS unsigned*)(lds + (bufoff) + ldsw + _i * 8192), 16, 0, 0); } while (0)
; #define PG8_LDA(dst, b, h) do { _Pragma("unroll") for (int m = 0; m < 4; ++m) _Pragma("unroll") for (int k = 0; k < 2; ++k) dst[m][k] = *(const PG8_LAS bf16x8*)(lds + PG8_SA(b, h) + aoff + m * 2048 + k * 1024); } while (0)
; #define PG8_LDB(dst, b, h) do { _Pragma("unroll") for (int n = 0; n < 2; ++n) _Pragma("unroll") for (int k = 0; k < 2; ++k) dst[n][k] = *(const PG8_LAS bf16x8*)(lds + PG8_SB(b, h) + boff + n * 2048 + k * 1024); } while (0)
; #define PG8_MMA(ai, bj, At, Bt) do { __builtin_amdgcn_s_setprio(1); _Pragma("unroll") for (int m = 0; m < 4; ++m) _Pragma("unroll") for (int n = 0; n < 2; ++n) _Pragma("unroll") for (int k = 0; k < 2; ++k) \
;         acc[ai][bj][m][n] = __builtin_amdgcn_mfma_f32_16x16x32_bf16(Bt[n][k], At[m][k], acc[ai][bj][m][n], 0, 0, 0); __builtin_amdgcn_s_setprio(0); } while (0)
; #define PG8_WAIT_V(n) asm volatile("s_waitcnt vmcnt(" #n ")" ::: "memory")
; #define PG8_WAIT_L(n) asm volatile("s_waitcnt lgkmcnt(" #n ")" ::: "memory")
; template <class Epi, class Sched, bool ALIGN_EPI = false, bool SP2 = false>
; __device__ __forceinline__ void gemm_phase(PG8_LAS unsigned char* lds, const Gemm g, const Sched& S, const Epi& E, int wave_in) {
;     ...
;             const bool last = (t == nt - 2);
;             const char* a1 = cA + (size_t)(t + 1) * kstep;
;             const char* a2 = last ? nA : cA + (size_t)(t + 2) * kstep; const char* b2 = last ? nB : cB + (size_t)(t + 2) * kstep;
;             const char* a3 = a2 + kstep; const char* b3 = b2 + kstep;
;             if (last && has_next) S.a_ready(nxt);
;             if constexpr (SP2) {
;             PG8_LDB(B0, 0, 0); PG8_LDB(B1, 0, 1); PG8_SCHED; PG8_LDA(At, 0, 0); PG8_STAGE(PG8_SA(1, 1), a1 + hstepA, voffA);
;             PG8_WAIT_V(8); PG8_WAIT_L(0); PG8_BAR; PG8_MMA(0, 0, At, B0); PG8_MMA(0, 1, At, B1); PG8_BAR; PG8_SCHED;
;             PG8_LDA(At, 0, 1); PG8_STAGE(PG8_SB(0, 0), b2, voffB); PG8_STAGE(PG8_SB(0, 1), b2 + hstep, voffB); PG8_STAGE(PG8_SA(0, 0), a2, voffA);
;             PG8_WAIT_V(8); PG8_WAIT_L(0); PG8_BAR; PG8_MMA(1, 0, At, B0); PG8_MMA(1, 1, At, B1); PG8_BAR; PG8_SCHED;
.LBB0_277:
	s_add_u32 s2, s0, 0xfff80080
	s_addc_u32 s3, s1, -1
	s_add_i32 s41, 0, 0x10000
	s_cmp_eq_u32 s40, 28
	s_cselect_b32 s5, s19, s3
	s_cselect_b32 s4, s36, s2
	s_cselect_b32 s3, s17, s39
	s_cselect_b32 s2, s37, s38
	s_add_i32 s44, 0, 0x14000
	v_add_u32_e32 v46, s41, v181
	v_add_u32_e32 v156, s44, v181
	ds_read_b128 v[26:29], v46
	ds_read_b128 v[30:33], v46 offset:1024
	ds_read_b128 v[42:45], v46 offset:2048
	ds_read_b128 v[46:49], v46 offset:3072
	ds_read_b128 v[168:171], v156
	ds_read_b128 v[172:175], v156 offset:1024
	ds_read_b128 v[176:179], v156 offset:2048
	ds_read_b128 v[184:187], v156 offset:3072
	s_add_i32 m0, s25, 0xc000
	ds_read_b128 v[188:191], v183
	ds_read_b128 v[212:215], v183 offset:1024
	ds_read_b128 v[216:219], v183 offset:2048
	ds_read_b128 v[220:223], v183 offset:3072
	ds_read_b128 v[224:227], v183 offset:4096
	ds_read_b128 v[228:231], v183 offset:5120
	ds_read_b128 v[232:235], v183 offset:6144
	global_load_lds_dwordx4 v152, s[0:1]
	s_add_i32 m0, s25, 0xe000
	ds_read_b128 v[236:239], v183 offset:7168
	global_load_lds_dwordx4 v154, s[0:1]
	s_waitcnt vmcnt(8)
	s_waitcnt lgkmcnt(0)
	s_barrier
	s_waitcnt lgkmcnt(0)
	v_mfma_f32_16x16x32_bf16 v[142:145], v[26:29], v[188:191], v[142:145]
	v_mfma_f32_16x16x32_bf16 v[138:141], v[42:45], v[188:191], v[138:141]
	v_mfma_f32_16x16x32_bf16 v[126:129], v[26:29], v[216:219], v[126:129]
	v_mfma_f32_16x16x32_bf16 v[122:125], v[42:45], v[216:219], v[122:125]
	v_mfma_f32_16x16x32_bf16 v[110:113], v[26:29], v[224:227], v[110:113]
	v_mfma_f32_16x16x32_bf16 v[106:109], v[42:45], v[224:227], v[106:109]
	v_mfma_f32_16x16x32_bf16 v[94:97], v[26:29], v[232:235], v[94:97]
	v_mfma_f32_16x16x32_bf16 v[90:93], v[42:45], v[232:235], v[90:93]
	v_mfma_f32_16x16x32_bf16 v[142:145], v[30:33], v[212:215], v[142:145]
	v_mfma_f32_16x16x32_bf16 v[138:141], v[46:49], v[212:215], v[138:141]
	v_mfma_f32_16x16x32_bf16 v[126:129], v[30:33], v[220:223], v[126:129]
	v_mfma_f32_16x16x32_bf16 v[122:125], v[46:49], v[220:223], v[122:125]
	v_mfma_f32_16x16x32_bf16 v[110:113], v[30:33], v[228:231], v[110:113]
	v_mfma_f32_16x16x32_bf16 v[106:109], v[46:49], v[228:231], v[106:109]
	v_mfma_f32_16x16x32_bf16 v[94:97], v[30:33], v[236:239], v[94:97]
	v_mfma_f32_16x16x32_bf16 v[90:93], v[46:49], v[236:239], v[90:93]
	v_mfma_f32_16x16x32_bf16 v[134:137], v[168:171], v[188:191], v[134:137]
	v_mfma_f32_16x16x32_bf16 v[130:133], v[176:179], v[188:191], v[130:133]
	v_mfma_f32_16x16x32_bf16 v[118:121], v[168:171], v[216:219], v[118:121]
	v_mfma_f32_16x16x32_bf16 v[114:117], v[176:179], v[216:219], v[114:117]
	v_mfma_f32_16x16x32_bf16 v[102:105], v[168:171], v[224:227], v[102:105]
	v_mfma_f32_16x16x32_bf16 v[98:101], v[176:179], v[224:227], v[98:101]
	v_mfma_f32_16x16x32_bf16 v[86:89], v[168:171], v[232:235], v[86:89]
	v_mfma_f32_16x16x32_bf16 v[82:85], v[176:179], v[232:235], v[82:85]
	v_mfma_f32_16x16x32_bf16 v[134:137], v[172:175], v[212:215], v[134:137]
	v_mfma_f32_16x16x32_bf16 v[130:133], v[184:187], v[212:215], v[130:133]
	v_mfma_f32_16x16x32_bf16 v[118:121], v[172:175], v[220:223], v[118:121]
	v_mfma_f32_16x16x32_bf16 v[114:117], v[184:187], v[220:223], v[114:117]
	v_mfma_f32_16x16x32_bf16 v[102:105], v[172:175], v[228:231], v[102:105]
	v_mfma_f32_16x16x32_bf16 v[98:101], v[184:187], v[228:231], v[98:101]
	v_mfma_f32_16x16x32_bf16 v[86:89], v[172:175], v[236:239], v[86:89]
	v_mfma_f32_16x16x32_bf16 v[82:85], v[184:187], v[236:239], v[82:85]
	s_barrier
	s_add_i32 s41, s41, s24
	s_add_u32 vcc_lo, s2, s84
	s_addc_u32 vcc_hi, s3, s85
	s_mov_b32 m0, s41
	ds_read_b128 v[188:191], v183 offset:16384
	ds_read_b128 v[212:215], v183 offset:17408
	ds_read_b128 v[216:219], v183 offset:18432
	ds_read_b128 v[220:223], v183 offset:19456
	ds_read_b128 v[224:227], v183 offset:20480
	global_load_lds_dwordx4 v0, s[2:3]
	s_add_i32 m0, s41, 0x2000
	s_add_u32 s42, s2, 0x80000
	s_addc_u32 s43, s3, 0
	s_add_i32 s41, s44, s24
	global_load_lds_dwordx4 v146, s[2:3]
	s_mov_b32 m0, s41
	s_add_u32 s98, s4, s84
	s_addc_u32 s99, s5, s85
	global_load_lds_dwordx4 v0, s[42:43]
	s_add_i32 m0, s41, 0x2000
	ds_read_b128 v[228:231], v183 offset:21504
	global_load_lds_dwordx4 v146, s[42:43]
	s_mov_b32 m0, s25
	ds_read_b128 v[232:235], v183 offset:22528
	global_load_lds_dwordx4 v150, s[4:5]
	s_mov_b32 m0, s26
	ds_read_b128 v[236:239], v183 offset:23552
	global_load_lds_dwordx4 v148, s[4:5]
	s_waitcnt vmcnt(8)
	s_waitcnt lgkmcnt(0)
	s_barrier
	s_waitcnt lgkmcnt(0)
	v_mfma_f32_16x16x32_bf16 v[78:81], v[26:29], v[188:191], v[78:81]
	v_mfma_f32_16x16x32_bf16 v[74:77], v[42:45], v[188:191], v[74:77]
	v_mfma_f32_16x16x32_bf16 v[62:65], v[26:29], v[216:219], v[62:65]
	v_mfma_f32_16x16x32_bf16 v[58:61], v[42:45], v[216:219], v[58:61]
	v_mfma_f32_16x16x32_bf16 v[38:41], v[26:29], v[224:227], v[38:41]
	v_mfma_f32_16x16x32_bf16 v[34:37], v[42:45], v[224:227], v[34:37]
	v_mfma_f32_16x16x32_bf16 v[14:17], v[26:29], v[232:235], v[14:17]
	v_mfma_f32_16x16x32_bf16 v[10:13], v[42:45], v[232:235], v[10:13]
	v_mfma_f32_16x16x32_bf16 v[78:81], v[30:33], v[212:215], v[78:81]
	v_mfma_f32_16x16x32_bf16 v[74:77], v[46:49], v[212:215], v[74:77]
	v_mfma_f32_16x16x32_bf16 v[62:65], v[30:33], v[220:223], v[62:65]
	v_mfma_f32_16x16x32_bf16 v[58:61], v[46:49], v[220:223], v[58:61]
	v_mfma_f32_16x16x32_bf16 v[38:41], v[30:33], v[228:231], v[38:41]
	v_mfma_f32_16x16x32_bf16 v[34:37], v[46:49], v[228:231], v[34:37]
	v_mfma_f32_16x16x32_bf16 v[14:17], v[30:33], v[236:239], v[14:17]
	v_mfma_f32_16x16x32_bf16 v[10:13], v[46:49], v[236:239], v[10:13]
	v_mfma_f32_16x16x32_bf16 v[22:25], v[168:171], v[224:227], v[22:25]
	v_mfma_f32_16x16x32_bf16 v[18:21], v[176:179], v[224:227], v[18:21]
	v_mfma_f32_16x16x32_bf16 v[6:9], v[168:171], v[232:235], v[6:9]
	v_mfma_f32_16x16x32_bf16 v[2:5], v[176:179], v[232:235], v[2:5]
	v_mfma_f32_16x16x32_bf16 v[26:29], v[168:171], v[188:191], v[70:73]
	v_mfma_f32_16x16x32_bf16 v[30:33], v[176:179], v[188:191], v[66:69]
	v_mfma_f32_16x16x32_bf16 v[42:45], v[168:171], v[216:219], v[54:57]
	v_mfma_f32_16x16x32_bf16 v[46:49], v[176:179], v[216:219], v[50:53]
	v_mfma_f32_16x16x32_bf16 v[22:25], v[172:175], v[228:231], v[22:25]
	v_mfma_f32_16x16x32_bf16 v[18:21], v[184:187], v[228:231], v[18:21]
	v_mfma_f32_16x16x32_bf16 v[6:9], v[172:175], v[236:239], v[6:9]
	v_mfma_f32_16x16x32_bf16 v[2:5], v[184:187], v[236:239], v[2:5]
	v_mfma_f32_16x16x32_bf16 v[26:29], v[172:175], v[212:215], v[26:29]
	v_mfma_f32_16x16x32_bf16 v[30:33], v[184:187], v[212:215], v[30:33]
	v_mfma_f32_16x16x32_bf16 v[42:45], v[172:175], v[220:223], v[42:45]
	v_mfma_f32_16x16x32_bf16 v[46:49], v[184:187], v[220:223], v[46:49]
	s_barrier
; #define PG8_STAGE(bufoff, gbase, voff) do { _Pragma("unroll") for (int _i = 0; _i < 2; ++_i) \
;         __builtin_amdgcn_global_load_lds((const unsigned*)((const char*)(gbase) + (voff)[_i]), (PG8_LAS unsigned*)(lds + (bufoff) + ldsw + _i * 8192), 16, 0, 0); } while (0)
; #define PG8_LDA(dst, b, h) do { _Pragma("unroll") for (int m = 0; m < 4; ++m) _Pragma("unroll") for (int k = 0; k < 2; ++k) dst[m][k] = *(const PG8_LAS bf16x8*)(lds + PG8_SA(b, h) + aoff + m * 2048 + k * 1024); } while (0)
; #define PG8_LDB(dst, b, h) do { _Pragma("unroll") for (int n = 0; n < 2; ++n) _Pragma("unroll") for (int k = 0; k < 2; ++k) dst[n][k] = *(const PG8_LAS bf16x8*)(lds + PG8_SB(b, h) + boff + n * 2048 + k * 1024); } while (0)
; #define PG8_MMA(ai, bj, At, Bt) do { __builtin_amdgcn_s_setprio(1); _Pragma("unroll") for (int m = 0; m < 4; ++m) _Pragma("unroll") for (int n = 0; n < 2; ++n) _Pragma("unroll") for (int k = 0; k < 2; ++k) \
;         acc[ai][bj][m][n] = __builtin_amdgcn_mfma_f32_16x16x32_bf16(Bt[n][k], At[m][k], acc[ai][bj][m][n], 0, 0, 0); __builtin_amdgcn_s_setprio(0); } while (0)
; #define PG8_WAIT_V(n) asm volatile("s_waitcnt vmcnt(" #n ")" ::: "memory")
; #define PG8_WAIT_L(n) asm volatile("s_waitcnt lgkmcnt(" #n ")" ::: "memory")
; #define PG8_BAR __builtin_amdgcn_s_barrier()
; template <class Epi, class Sched, bool ALIGN_EPI = false, bool SP2 = false>
; __device__ __forceinline__ void gemm_phase(PG8_LAS unsigned char* lds, const Gemm g, const Sched& S, const Epi& E, int wave_in) {
;     ...
;         for (int t = 0; t < nt; t += 2) {
;             const bool last = (t == nt - 2);
;             const char* a1 = cA + (size_t)(t + 1) * kstep;
;             const char* a2 = last ? nA : cA + (size_t)(t + 2) * kstep; const char* b2 = last ? nB : cB + (size_t)(t + 2) * kstep;
;             const char* a3 = a2 + kstep; const char* b3 = b2 + kstep;
;     ...
;             PG8_LDB(B0, 1, 0); PG8_LDB(B1, 1, 1); PG8_SCHED; PG8_LDA(At, 1, 0); PG8_STAGE(PG8_SA(0, 1), a2 + hstepA, voffA);
;             PG8_WAIT_V(8); PG8_WAIT_L(0); PG8_BAR; PG8_MMA(0, 0, At, B0); PG8_MMA(0, 1, At, B1); PG8_BAR; PG8_SCHED;
;             PG8_LDA(At, 1, 1); PG8_STAGE(PG8_SB(1, 0), b3, voffB); PG8_STAGE(PG8_SB(1, 1), b3 + hstep, voffB); PG8_STAGE(PG8_SA(1, 0), a3, voffA);
;             PG8_WAIT_V(8); PG8_WAIT_L(0); PG8_BAR; PG8_MMA(1, 0, At, B0); PG8_MMA(1, 1, At, B1); PG8_BAR; PG8_SCHED;
	s_add_i32 s41, 0, 0x18000
	s_add_i32 s42, 0, 0x1c000
	v_add_u32_e32 v70, s41, v181
	v_add_u32_e32 v184, s42, v181
	ds_read_b128 v[50:53], v70
	ds_read_b128 v[54:57], v70 offset:1024
	ds_read_b128 v[66:69], v70 offset:2048
	ds_read_b128 v[70:73], v70 offset:3072
	ds_read_b128 v[168:171], v184
	ds_read_b128 v[172:175], v184 offset:1024
	ds_read_b128 v[176:179], v184 offset:2048
	ds_read_b128 v[184:187], v184 offset:3072
	s_add_u32 s4, s4, 0x80000
	s_addc_u32 s5, s5, 0
	s_mov_b32 m0, s27
	ds_read_b128 v[188:191], v183 offset:32768
	ds_read_b128 v[212:215], v183 offset:33792
	ds_read_b128 v[216:219], v183 offset:34816
	ds_read_b128 v[220:223], v183 offset:35840
	ds_read_b128 v[224:227], v183 offset:36864
	ds_read_b128 v[228:231], v183 offset:37888
	ds_read_b128 v[232:235], v183 offset:38912
	global_load_lds_dwordx4 v150, s[4:5]
	s_mov_b32 m0, s28
	ds_read_b128 v[236:239], v183 offset:39936
	global_load_lds_dwordx4 v148, s[4:5]
	s_waitcnt vmcnt(8)
	s_waitcnt lgkmcnt(0)
	s_barrier
	s_waitcnt lgkmcnt(0)
	v_mfma_f32_16x16x32_bf16 v[142:145], v[50:53], v[188:191], v[142:145]
	v_mfma_f32_16x16x32_bf16 v[138:141], v[66:69], v[188:191], v[138:141]
	v_mfma_f32_16x16x32_bf16 v[126:129], v[50:53], v[216:219], v[126:129]
	v_mfma_f32_16x16x32_bf16 v[122:125], v[66:69], v[216:219], v[122:125]
	v_mfma_f32_16x16x32_bf16 v[110:113], v[50:53], v[224:227], v[110:113]
	v_mfma_f32_16x16x32_bf16 v[106:109], v[66:69], v[224:227], v[106:109]
	v_mfma_f32_16x16x32_bf16 v[94:97], v[50:53], v[232:235], v[94:97]
	v_mfma_f32_16x16x32_bf16 v[90:93], v[66:69], v[232:235], v[90:93]
	v_mfma_f32_16x16x32_bf16 v[142:145], v[54:57], v[212:215], v[142:145]
	v_mfma_f32_16x16x32_bf16 v[138:141], v[70:73], v[212:215], v[138:141]
	v_mfma_f32_16x16x32_bf16 v[126:129], v[54:57], v[220:223], v[126:129]
	v_mfma_f32_16x16x32_bf16 v[122:125], v[70:73], v[220:223], v[122:125]
	v_mfma_f32_16x16x32_bf16 v[110:113], v[54:57], v[228:231], v[110:113]
	v_mfma_f32_16x16x32_bf16 v[106:109], v[70:73], v[228:231], v[106:109]
	v_mfma_f32_16x16x32_bf16 v[94:97], v[54:57], v[236:239], v[94:97]
	v_mfma_f32_16x16x32_bf16 v[90:93], v[70:73], v[236:239], v[90:93]
	v_mfma_f32_16x16x32_bf16 v[134:137], v[168:171], v[188:191], v[134:137]
	v_mfma_f32_16x16x32_bf16 v[130:133], v[176:179], v[188:191], v[130:133]
	v_mfma_f32_16x16x32_bf16 v[118:121], v[168:171], v[216:219], v[118:121]
	v_mfma_f32_16x16x32_bf16 v[114:117], v[176:179], v[216:219], v[114:117]
	v_mfma_f32_16x16x32_bf16 v[102:105], v[168:171], v[224:227], v[102:105]
	v_mfma_f32_16x16x32_bf16 v[98:101], v[176:179], v[224:227], v[98:101]
	v_mfma_f32_16x16x32_bf16 v[86:89], v[168:171], v[232:235], v[86:89]
	v_mfma_f32_16x16x32_bf16 v[82:85], v[176:179], v[232:235], v[82:85]
	v_mfma_f32_16x16x32_bf16 v[134:137], v[172:175], v[212:215], v[134:137]
	v_mfma_f32_16x16x32_bf16 v[130:133], v[184:187], v[212:215], v[130:133]
	v_mfma_f32_16x16x32_bf16 v[118:121], v[172:175], v[220:223], v[118:121]
	v_mfma_f32_16x16x32_bf16 v[114:117], v[184:187], v[220:223], v[114:117]
	v_mfma_f32_16x16x32_bf16 v[102:105], v[172:175], v[228:231], v[102:105]
	v_mfma_f32_16x16x32_bf16 v[98:101], v[184:187], v[228:231], v[98:101]
	v_mfma_f32_16x16x32_bf16 v[86:89], v[172:175], v[236:239], v[86:89]
	v_mfma_f32_16x16x32_bf16 v[82:85], v[184:187], v[236:239], v[82:85]
	s_barrier
	s_add_i32 s4, s41, s24
	s_mov_b32 m0, s4
	ds_read_b128 v[188:191], v183 offset:49152
	ds_read_b128 v[212:215], v183 offset:50176
	ds_read_b128 v[216:219], v183 offset:51200
	ds_read_b128 v[220:223], v183 offset:52224
	global_load_lds_dwordx4 v0, vcc
	s_add_i32 m0, s4, 0x2000
	s_add_u32 s2, s2, 0x80080
	s_addc_u32 s3, s3, 0
	s_add_i32 s4, s42, s24
	global_load_lds_dwordx4 v146, vcc
	s_mov_b32 m0, s4
	ds_read_b128 v[224:227], v183 offset:53248
	global_load_lds_dwordx4 v0, s[2:3]
	s_add_i32 m0, s4, 0x2000
	ds_read_b128 v[228:231], v183 offset:54272
	global_load_lds_dwordx4 v146, s[2:3]
	s_mov_b32 m0, s29
	ds_read_b128 v[232:235], v183 offset:55296
	global_load_lds_dwordx4 v150, s[98:99]
	s_mov_b32 m0, s30
	ds_read_b128 v[236:239], v183 offset:56320
	global_load_lds_dwordx4 v148, s[98:99]
	s_waitcnt vmcnt(8)
	s_waitcnt lgkmcnt(0)
	s_barrier
	s_waitcnt lgkmcnt(0)
	v_mfma_f32_16x16x32_bf16 v[78:81], v[50:53], v[188:191], v[78:81]
	v_mfma_f32_16x16x32_bf16 v[74:77], v[66:69], v[188:191], v[74:77]
	v_mfma_f32_16x16x32_bf16 v[62:65], v[50:53], v[216:219], v[62:65]
	v_mfma_f32_16x16x32_bf16 v[58:61], v[66:69], v[216:219], v[58:61]
	v_mfma_f32_16x16x32_bf16 v[38:41], v[50:53], v[224:227], v[38:41]
	v_mfma_f32_16x16x32_bf16 v[34:37], v[66:69], v[224:227], v[34:37]
	v_mfma_f32_16x16x32_bf16 v[14:17], v[50:53], v[232:235], v[14:17]
	v_mfma_f32_16x16x32_bf16 v[10:13], v[66:69], v[232:235], v[10:13]
	v_mfma_f32_16x16x32_bf16 v[78:81], v[54:57], v[212:215], v[78:81]
	v_mfma_f32_16x16x32_bf16 v[74:77], v[70:73], v[212:215], v[74:77]
	v_mfma_f32_16x16x32_bf16 v[62:65], v[54:57], v[220:223], v[62:65]
	v_mfma_f32_16x16x32_bf16 v[58:61], v[70:73], v[220:223], v[58:61]
	v_mfma_f32_16x16x32_bf16 v[38:41], v[54:57], v[228:231], v[38:41]
	v_mfma_f32_16x16x32_bf16 v[34:37], v[70:73], v[228:231], v[34:37]
	v_mfma_f32_16x16x32_bf16 v[14:17], v[54:57], v[236:239], v[14:17]
	v_mfma_f32_16x16x32_bf16 v[10:13], v[70:73], v[236:239], v[10:13]
	v_mfma_f32_16x16x32_bf16 v[26:29], v[168:171], v[188:191], v[26:29]
	v_mfma_f32_16x16x32_bf16 v[70:73], v[172:175], v[212:215], v[26:29]
	v_mfma_f32_16x16x32_bf16 v[26:29], v[176:179], v[188:191], v[30:33]
	v_mfma_f32_16x16x32_bf16 v[66:69], v[184:187], v[212:215], v[26:29]
	v_mfma_f32_16x16x32_bf16 v[26:29], v[168:171], v[216:219], v[42:45]
	v_mfma_f32_16x16x32_bf16 v[54:57], v[172:175], v[220:223], v[26:29]
	v_mfma_f32_16x16x32_bf16 v[26:29], v[176:179], v[216:219], v[46:49]
	v_mfma_f32_16x16x32_bf16 v[22:25], v[168:171], v[224:227], v[22:25]
	v_mfma_f32_16x16x32_bf16 v[18:21], v[176:179], v[224:227], v[18:21]
	v_mfma_f32_16x16x32_bf16 v[6:9], v[168:171], v[232:235], v[6:9]
	v_mfma_f32_16x16x32_bf16 v[2:5], v[176:179], v[232:235], v[2:5]
	v_mfma_f32_16x16x32_bf16 v[50:53], v[184:187], v[220:223], v[26:29]
	v_mfma_f32_16x16x32_bf16 v[22:25], v[172:175], v[228:231], v[22:25]
	v_mfma_f32_16x16x32_bf16 v[18:21], v[184:187], v[228:231], v[18:21]
	v_mfma_f32_16x16x32_bf16 v[6:9], v[172:175], v[236:239], v[6:9]
	v_mfma_f32_16x16x32_bf16 v[2:5], v[184:187], v[236:239], v[2:5]
	s_barrier
	s_add_i32 s40, s40, 2
	s_add_u32 s0, s0, 0x100
	s_addc_u32 s1, s1, 0
	s_add_u32 s38, s38, 0x100
	s_addc_u32 s39, s39, 0
	s_cmp_gt_u32 s40, 29
	s_cbranch_scc0 .LBB0_277
	s_and_b64 vcc, exec, s[14:15]
	s_cbranch_vccz .LBB0_280
	s_barrier

; template <class Epi, class Sched, bool ALIGN_EPI = false, bool SP2 = false>
; __device__ __forceinline__ void gemm_phase(PG8_LAS unsigned char* lds, const Gemm g, const Sched& S, const Epi& E, int wave_in) {
;     ...
; #pragma unroll
;         for (int a = 0; a < 2; ++a)
; #pragma unroll
;             for (int b = 0; b < 2; ++b)
; #pragma unroll
;                 for (int m = 0; m < 4; ++m)
; #pragma unroll
;                     for (int n = 0; n < 2; ++n) acc[a][b][m][n] = (f32x4){0.f, 0.f, 0.f, 0.f};
;         cur = nxt; cA = nA; cB = nB; ++ui;
.LBB0_403:
	s_add_u32 s4, s24, 0x80
	s_addc_u32 s5, s25, 0
	s_add_u32 s24, s6, 0x100
	v_mov_b32_e32 v2, 0
	s_addc_u32 s25, s7, 0
	s_mov_b32 s6, 0
	v_mov_b32_e32 v3, v2
	v_mov_b32_e32 v4, v2
	v_mov_b32_e32 v5, v2
	v_mov_b32_e32 v6, v2
	s_waitcnt lgkmcnt(0)
	v_mov_b32_e32 v7, v2
	v_mov_b32_e32 v8, v2
	v_mov_b32_e32 v9, v2
	v_mov_b32_e32 v18, v2
	v_mov_b32_e32 v19, v2
	v_mov_b32_e32 v20, v2
	v_mov_b32_e32 v21, v2
	v_mov_b32_e32 v22, v2
	v_mov_b32_e32 v23, v2
	s_waitcnt vmcnt(0)
	v_mov_b32_e32 v24, v2
	v_mov_b32_e32 v25, v2
	v_mov_b32_e32 v34, v2
	v_mov_b32_e32 v35, v2
	v_mov_b32_e32 v36, v2
	v_mov_b32_e32 v37, v2
	v_mov_b32_e32 v38, v2
	v_mov_b32_e32 v39, v2
	v_mov_b32_e32 v40, v2
	v_mov_b32_e32 v41, v2
	v_mov_b32_e32 v50, v2
	v_mov_b32_e32 v51, v2
	v_mov_b32_e32 v52, v2
	v_mov_b32_e32 v53, v2
	v_mov_b32_e32 v54, v2
	v_mov_b32_e32 v55, v2
	v_mov_b32_e32 v56, v2
	v_mov_b32_e32 v57, v2
	v_mov_b32_e32 v10, v2
	v_mov_b32_e32 v11, v2
	v_mov_b32_e32 v12, v2
	v_mov_b32_e32 v13, v2
	v_mov_b32_e32 v14, v2
	v_mov_b32_e32 v15, v2
	v_mov_b32_e32 v16, v2
	v_mov_b32_e32 v17, v2
	v_mov_b32_e32 v26, v2
	v_mov_b32_e32 v27, v2
	v_mov_b32_e32 v28, v2
	v_mov_b32_e32 v29, v2
	v_mov_b32_e32 v30, v2
	v_mov_b32_e32 v31, v2
	v_mov_b32_e32 v32, v2
	v_mov_b32_e32 v33, v2
	v_mov_b32_e32 v42, v2
	v_mov_b32_e32 v43, v2
	v_mov_b32_e32 v44, v2
	v_mov_b32_e32 v45, v2
	v_mov_b32_e32 v46, v2
	v_mov_b32_e32 v47, v2
	v_mov_b32_e32 v48, v2
	v_mov_b32_e32 v49, v2
	v_mov_b32_e32 v58, v2
	v_mov_b32_e32 v59, v2
	v_mov_b32_e32 v60, v2
	v_mov_b32_e32 v61, v2
	v_mov_b32_e32 v62, v2
	v_mov_b32_e32 v63, v2
	v_mov_b32_e32 v64, v2
	v_mov_b32_e32 v65, v2
	v_mov_b32_e32 v66, v2
	v_mov_b32_e32 v67, v2
	v_mov_b32_e32 v68, v2
	v_mov_b32_e32 v69, v2
	v_mov_b32_e32 v70, v2
	v_mov_b32_e32 v71, v2
	v_mov_b32_e32 v72, v2
	v_mov_b32_e32 v73, v2
	v_mov_b32_e32 v82, v2
	v_mov_b32_e32 v83, v2
	v_mov_b32_e32 v84, v2
	v_mov_b32_e32 v85, v2
	v_mov_b32_e32 v86, v2
	v_mov_b32_e32 v87, v2
	v_mov_b32_e32 v88, v2
	v_mov_b32_e32 v89, v2
	v_mov_b32_e32 v98, v2
	v_mov_b32_e32 v99, v2
	v_mov_b32_e32 v100, v2
	v_mov_b32_e32 v101, v2
	v_mov_b32_e32 v102, v2
	v_mov_b32_e32 v103, v2
	v_mov_b32_e32 v104, v2
	v_mov_b32_e32 v105, v2
	v_mov_b32_e32 v114, v2
	v_mov_b32_e32 v115, v2
	v_mov_b32_e32 v116, v2
	v_mov_b32_e32 v117, v2
	v_mov_b32_e32 v118, v2
	v_mov_b32_e32 v119, v2
	v_mov_b32_e32 v120, v2
	v_mov_b32_e32 v121, v2
	v_mov_b32_e32 v74, v2
	v_mov_b32_e32 v75, v2
	v_mov_b32_e32 v76, v2
	v_mov_b32_e32 v77, v2
	v_mov_b32_e32 v78, v2
	v_mov_b32_e32 v79, v2
	v_mov_b32_e32 v80, v2
	v_mov_b32_e32 v81, v2
	v_mov_b32_e32 v90, v2
	v_mov_b32_e32 v91, v2
	v_mov_b32_e32 v92, v2
	v_mov_b32_e32 v93, v2
	v_mov_b32_e32 v94, v2
	v_mov_b32_e32 v95, v2
	v_mov_b32_e32 v96, v2
	v_mov_b32_e32 v97, v2
	v_mov_b32_e32 v106, v2
	v_mov_b32_e32 v107, v2
	v_mov_b32_e32 v108, v2
	v_mov_b32_e32 v109, v2
	v_mov_b32_e32 v110, v2
	v_mov_b32_e32 v111, v2
	v_mov_b32_e32 v112, v2
	v_mov_b32_e32 v113, v2
	v_mov_b32_e32 v122, v2
	v_mov_b32_e32 v123, v2
	v_mov_b32_e32 v124, v2
	v_mov_b32_e32 v125, v2
	v_mov_b32_e32 v126, v2
	v_mov_b32_e32 v127, v2
	v_mov_b32_e32 v128, v2
	v_mov_b32_e32 v129, v2
	s_nop 0
	s_nop 0
	s_nop 0
	s_nop 0
	s_nop 0
	s_nop 0
	s_nop 0
	s_nop 0
	s_nop 0
	s_nop 0
	s_nop 0
	s_nop 0
	s_nop 0
	s_nop 0

; #define PG8_STAGE(bufoff, gbase, voff) do { _Pragma("unroll") for (int _i = 0; _i < 2; ++_i) \
;         __builtin_amdgcn_global_load_lds((const unsigned*)((const char*)(gbase) + (voff)[_i]), (PG8_LAS unsigned*)(lds + (bufoff) + ldsw + _i * 8192), 16, 0, 0); } while (0)
; #define PG8_LDA(dst, b, h) do { _Pragma("unroll") for (int m = 0; m < 4; ++m) _Pragma("unroll") for (int k = 0; k < 2; ++k) dst[m][k] = *(const PG8_LAS bf16x8*)(lds + PG8_SA(b, h) + aoff + m * 2048 + k * 1024); } while (0)
; #define PG8_LDB(dst, b, h) do { _Pragma("unroll") for (int n = 0; n < 2; ++n) _Pragma("unroll") for (int k = 0; k < 2; ++k) dst[n][k] = *(const PG8_LAS bf16x8*)(lds + PG8_SB(b, h) + boff + n * 2048 + k * 1024); } while (0)
; #define PG8_MMA(ai, bj, At, Bt) do { __builtin_amdgcn_s_setprio(1); _Pragma("unroll") for (int m = 0; m < 4; ++m) _Pragma("unroll") for (int n = 0; n < 2; ++n) _Pragma("unroll") for (int k = 0; k < 2; ++k) \
;         acc[ai][bj][m][n] = __builtin_amdgcn_mfma_f32_16x16x32_bf16(Bt[n][k], At[m][k], acc[ai][bj][m][n], 0, 0, 0); __builtin_amdgcn_s_setprio(0); } while (0)
; #define PG8_WAIT_V(n) asm volatile("s_waitcnt vmcnt(" #n ")" ::: "memory")
; #define PG8_WAIT_L(n) asm volatile("s_waitcnt lgkmcnt(" #n ")" ::: "memory")
; #define PG8_BAR __builtin_amdgcn_s_barrier()
; #define PG8_SCHED __builtin_amdgcn_sched_barrier(0)
; template <class Epi, class Sched, bool ALIGN_EPI = false, bool SP2 = false>
; __device__ __forceinline__ void gemm_phase(PG8_LAS unsigned char* lds, const Gemm g, const Sched& S, const Epi& E, int wave_in) {
;     ...
;             PG8_LDB(B0, 0, 0); PG8_LDB(B1, 0, 1); PG8_SCHED; PG8_LDA(At, 0, 0); PG8_STAGE(PG8_SA(1, 1), a1 + hstepA, voffA);
;             PG8_WAIT_V(8); PG8_WAIT_L(0); PG8_BAR; PG8_MMA(0, 0, At, B0); PG8_MMA(0, 1, At, B1); PG8_BAR; PG8_SCHED;
;             PG8_LDA(At, 0, 1); PG8_STAGE(PG8_SB(0, 0), b2, voffB); PG8_STAGE(PG8_SB(0, 1), b2 + hstep, voffB); PG8_STAGE(PG8_SA(0, 0), a2, voffA);
;             PG8_WAIT_V(8); PG8_WAIT_L(0); PG8_BAR; PG8_MMA(1, 0, At, B0); PG8_MMA(1, 1, At, B1); PG8_BAR; PG8_SCHED;
.Lmg_nohook:
	s_add_i32 s43, s6, 2
	s_add_u32 s44, s4, 0x80
	s_addc_u32 s7, s5, 0
	s_add_i32 s46, 0, 0x10000
	s_cmp_eq_u32 s37, s6
	s_cselect_b32 s7, s21, s7
	s_cselect_b32 s6, s20, s44
	s_cselect_b32 s45, s23, s25
	s_cselect_b32 s44, s22, s24
	s_add_i32 s47, 0, 0x14000
	v_add_u32_e32 v168, s46, v149
	v_add_u32_e32 v184, s47, v149
	ds_read_b128 v[140:143], v168
	ds_read_b128 v[144:147], v168 offset:1024
	ds_read_b128 v[154:157], v168 offset:2048
	ds_read_b128 v[168:171], v168 offset:3072
	ds_read_b128 v[172:175], v184
	ds_read_b128 v[176:179], v184 offset:1024
	ds_read_b128 v[180:183], v184 offset:2048
	ds_read_b128 v[184:187], v184 offset:3072
	v_lshl_add_u64 v[192:193], s[4:5], 0, v[136:137]
	s_add_i32 m0, s28, 0xc000
	ds_read_b128 v[188:191], v153
	ds_read_b128 v[212:215], v153 offset:1024
	ds_read_b128 v[216:219], v153 offset:2048
	ds_read_b128 v[220:223], v153 offset:3072
	ds_read_b128 v[224:227], v153 offset:4096
	ds_read_b128 v[228:231], v153 offset:5120
	ds_read_b128 v[232:235], v153 offset:6144
	global_load_lds_dwordx4 v[192:193], off
	v_lshl_add_u64 v[192:193], s[4:5], 0, v[138:139]
	s_add_i32 m0, s28, 0xe000
	ds_read_b128 v[236:239], v153 offset:7168
	global_load_lds_dwordx4 v[192:193], off
	s_waitcnt vmcnt(8)
	s_waitcnt lgkmcnt(0)
	s_barrier
	s_waitcnt lgkmcnt(0)
	v_mfma_f32_16x16x32_bf16 v[126:129], v[140:143], v[188:191], v[126:129]
	v_mfma_f32_16x16x32_bf16 v[122:125], v[154:157], v[188:191], v[122:125]
	v_mfma_f32_16x16x32_bf16 v[110:113], v[140:143], v[216:219], v[110:113]
	v_mfma_f32_16x16x32_bf16 v[106:109], v[154:157], v[216:219], v[106:109]
	v_mfma_f32_16x16x32_bf16 v[94:97], v[140:143], v[224:227], v[94:97]
	v_mfma_f32_16x16x32_bf16 v[90:93], v[154:157], v[224:227], v[90:93]
	v_mfma_f32_16x16x32_bf16 v[78:81], v[140:143], v[232:235], v[78:81]
	v_mfma_f32_16x16x32_bf16 v[74:77], v[154:157], v[232:235], v[74:77]
	v_mfma_f32_16x16x32_bf16 v[126:129], v[144:147], v[212:215], v[126:129]
	v_mfma_f32_16x16x32_bf16 v[122:125], v[168:171], v[212:215], v[122:125]
	v_mfma_f32_16x16x32_bf16 v[110:113], v[144:147], v[220:223], v[110:113]
	v_mfma_f32_16x16x32_bf16 v[106:109], v[168:171], v[220:223], v[106:109]
	v_mfma_f32_16x16x32_bf16 v[94:97], v[144:147], v[228:231], v[94:97]
	v_mfma_f32_16x16x32_bf16 v[90:93], v[168:171], v[228:231], v[90:93]
	v_mfma_f32_16x16x32_bf16 v[78:81], v[144:147], v[236:239], v[78:81]
	v_mfma_f32_16x16x32_bf16 v[74:77], v[168:171], v[236:239], v[74:77]
	v_mfma_f32_16x16x32_bf16 v[118:121], v[172:175], v[188:191], v[118:121]
	v_mfma_f32_16x16x32_bf16 v[114:117], v[180:183], v[188:191], v[114:117]
	v_mfma_f32_16x16x32_bf16 v[102:105], v[172:175], v[216:219], v[102:105]
	v_mfma_f32_16x16x32_bf16 v[98:101], v[180:183], v[216:219], v[98:101]
	v_mfma_f32_16x16x32_bf16 v[86:89], v[172:175], v[224:227], v[86:89]
	v_mfma_f32_16x16x32_bf16 v[82:85], v[180:183], v[224:227], v[82:85]
	v_mfma_f32_16x16x32_bf16 v[70:73], v[172:175], v[232:235], v[70:73]
	v_mfma_f32_16x16x32_bf16 v[66:69], v[180:183], v[232:235], v[66:69]
	v_mfma_f32_16x16x32_bf16 v[118:121], v[176:179], v[212:215], v[118:121]
	v_mfma_f32_16x16x32_bf16 v[114:117], v[184:187], v[212:215], v[114:117]
	v_mfma_f32_16x16x32_bf16 v[102:105], v[176:179], v[220:223], v[102:105]
	v_mfma_f32_16x16x32_bf16 v[98:101], v[184:187], v[220:223], v[98:101]
	v_mfma_f32_16x16x32_bf16 v[86:89], v[176:179], v[228:231], v[86:89]
	v_mfma_f32_16x16x32_bf16 v[82:85], v[184:187], v[228:231], v[82:85]
	v_mfma_f32_16x16x32_bf16 v[70:73], v[176:179], v[236:239], v[70:73]
	v_mfma_f32_16x16x32_bf16 v[66:69], v[184:187], v[236:239], v[66:69]
	s_barrier
	s_add_i32 s46, s46, s27
	v_lshl_add_u64 v[192:193], s[44:45], 0, v[0:1]
	s_mov_b32 m0, s46
	ds_read_b128 v[188:191], v153 offset:16384
	ds_read_b128 v[212:215], v153 offset:17408
	ds_read_b128 v[216:219], v153 offset:18432
	ds_read_b128 v[220:223], v153 offset:19456
	ds_read_b128 v[224:227], v153 offset:20480
	ds_read_b128 v[228:231], v153 offset:21504
	ds_read_b128 v[232:235], v153 offset:22528
	global_load_lds_dwordx4 v[192:193], off
	s_add_i32 m0, s46, 0x2000
	v_lshl_add_u64 v[200:201], s[44:45], 0, v[130:131]
	s_add_u32 s44, s44, s78
	s_addc_u32 s45, s45, 0
	s_add_i32 s46, s47, s27
	global_load_lds_dwordx4 v[200:201], off
	v_lshl_add_u64 v[240:241], s[44:45], 0, v[0:1]
	s_mov_b32 m0, s46
	v_lshl_add_u64 v[242:243], s[44:45], 0, v[130:131]
	global_load_lds_dwordx4 v[240:241], off
	s_add_i32 m0, s46, 0x2000
	v_lshl_add_u64 v[244:245], s[6:7], 0, v[134:135]
	global_load_lds_dwordx4 v[242:243], off
	s_mov_b32 m0, s28
	v_lshl_add_u64 v[246:247], s[6:7], 0, v[132:133]
	global_load_lds_dwordx4 v[244:245], off
	s_mov_b32 m0, s29
	ds_read_b128 v[236:239], v153 offset:23552
	global_load_lds_dwordx4 v[246:247], off
	s_waitcnt vmcnt(8)
	s_waitcnt lgkmcnt(0)
	s_barrier
; #define PG8_STAGE(bufoff, gbase, voff) do { _Pragma("unroll") for (int _i = 0; _i < 2; ++_i) \
;         __builtin_amdgcn_global_load_lds((const unsigned*)((const char*)(gbase) + (voff)[_i]), (PG8_LAS unsigned*)(lds + (bufoff) + ldsw + _i * 8192), 16, 0, 0); } while (0)
; #define PG8_LDA(dst, b, h) do { _Pragma("unroll") for (int m = 0; m < 4; ++m) _Pragma("unroll") for (int k = 0; k < 2; ++k) dst[m][k] = *(const PG8_LAS bf16x8*)(lds + PG8_SA(b, h) + aoff + m * 2048 + k * 1024); } while (0)
; #define PG8_LDB(dst, b, h) do { _Pragma("unroll") for (int n = 0; n < 2; ++n) _Pragma("unroll") for (int k = 0; k < 2; ++k) dst[n][k] = *(const PG8_LAS bf16x8*)(lds + PG8_SB(b, h) + boff + n * 2048 + k * 1024); } while (0)
; #define PG8_MMA(ai, bj, At, Bt) do { __builtin_amdgcn_s_setprio(1); _Pragma("unroll") for (int m = 0; m < 4; ++m) _Pragma("unroll") for (int n = 0; n < 2; ++n) _Pragma("unroll") for (int k = 0; k < 2; ++k) \
;         acc[ai][bj][m][n] = __builtin_amdgcn_mfma_f32_16x16x32_bf16(Bt[n][k], At[m][k], acc[ai][bj][m][n], 0, 0, 0); __builtin_amdgcn_s_setprio(0); } while (0)
; #define PG8_WAIT_V(n) asm volatile("s_waitcnt vmcnt(" #n ")" ::: "memory")
; #define PG8_WAIT_L(n) asm volatile("s_waitcnt lgkmcnt(" #n ")" ::: "memory")
; #define PG8_BAR __builtin_amdgcn_s_barrier()
; #define PG8_SCHED __builtin_amdgcn_sched_barrier(0)
; template <class Epi, class Sched, bool ALIGN_EPI = false, bool SP2 = false>
; __device__ __forceinline__ void gemm_phase(PG8_LAS unsigned char* lds, const Gemm g, const Sched& S, const Epi& E, int wave_in) {
;     ...
;             PG8_WAIT_V(8); PG8_WAIT_L(0); PG8_BAR; PG8_MMA(1, 0, At, B0); PG8_MMA(1, 1, At, B1); PG8_BAR; PG8_SCHED;
;             PG8_LDB(B0, 1, 0); PG8_LDB(B1, 1, 1); PG8_SCHED; PG8_LDA(At, 1, 0); PG8_STAGE(PG8_SA(0, 1), a2 + hstepA, voffA);
;             PG8_WAIT_V(8); PG8_WAIT_L(0); PG8_BAR; PG8_MMA(0, 0, At, B0); PG8_MMA(0, 1, At, B1); PG8_BAR; PG8_SCHED;
	s_waitcnt lgkmcnt(0)
	v_mfma_f32_16x16x32_bf16 v[62:65], v[140:143], v[188:191], v[62:65]
	v_mfma_f32_16x16x32_bf16 v[58:61], v[154:157], v[188:191], v[58:61]
	v_mfma_f32_16x16x32_bf16 v[46:49], v[140:143], v[216:219], v[46:49]
	v_mfma_f32_16x16x32_bf16 v[42:45], v[154:157], v[216:219], v[42:45]
	v_mfma_f32_16x16x32_bf16 v[30:33], v[140:143], v[224:227], v[30:33]
	v_mfma_f32_16x16x32_bf16 v[26:29], v[154:157], v[224:227], v[26:29]
	v_mfma_f32_16x16x32_bf16 v[14:17], v[140:143], v[232:235], v[14:17]
	v_mfma_f32_16x16x32_bf16 v[10:13], v[154:157], v[232:235], v[10:13]
	v_mfma_f32_16x16x32_bf16 v[62:65], v[144:147], v[212:215], v[62:65]
	v_mfma_f32_16x16x32_bf16 v[58:61], v[168:171], v[212:215], v[58:61]
	v_mfma_f32_16x16x32_bf16 v[46:49], v[144:147], v[220:223], v[46:49]
	v_mfma_f32_16x16x32_bf16 v[42:45], v[168:171], v[220:223], v[42:45]
	v_mfma_f32_16x16x32_bf16 v[30:33], v[144:147], v[228:231], v[30:33]
	v_mfma_f32_16x16x32_bf16 v[26:29], v[168:171], v[228:231], v[26:29]
	v_mfma_f32_16x16x32_bf16 v[14:17], v[144:147], v[236:239], v[14:17]
	v_mfma_f32_16x16x32_bf16 v[10:13], v[168:171], v[236:239], v[10:13]
	v_mfma_f32_16x16x32_bf16 v[54:57], v[172:175], v[188:191], v[54:57]
	v_mfma_f32_16x16x32_bf16 v[50:53], v[180:183], v[188:191], v[50:53]
	v_mfma_f32_16x16x32_bf16 v[38:41], v[172:175], v[216:219], v[38:41]
	v_mfma_f32_16x16x32_bf16 v[34:37], v[180:183], v[216:219], v[34:37]
	v_mfma_f32_16x16x32_bf16 v[22:25], v[172:175], v[224:227], v[22:25]
	v_mfma_f32_16x16x32_bf16 v[18:21], v[180:183], v[224:227], v[18:21]
	v_mfma_f32_16x16x32_bf16 v[6:9], v[172:175], v[232:235], v[6:9]
	v_mfma_f32_16x16x32_bf16 v[2:5], v[180:183], v[232:235], v[2:5]
	v_mfma_f32_16x16x32_bf16 v[54:57], v[176:179], v[212:215], v[54:57]
	v_mfma_f32_16x16x32_bf16 v[50:53], v[184:187], v[212:215], v[50:53]
	v_mfma_f32_16x16x32_bf16 v[38:41], v[176:179], v[220:223], v[38:41]
	v_mfma_f32_16x16x32_bf16 v[34:37], v[184:187], v[220:223], v[34:37]
	v_mfma_f32_16x16x32_bf16 v[22:25], v[176:179], v[228:231], v[22:25]
	v_mfma_f32_16x16x32_bf16 v[18:21], v[184:187], v[228:231], v[18:21]
	v_mfma_f32_16x16x32_bf16 v[6:9], v[176:179], v[236:239], v[6:9]
	v_mfma_f32_16x16x32_bf16 v[2:5], v[184:187], v[236:239], v[2:5]
	s_barrier
	s_add_i32 s44, 0, 0x18000
	s_add_i32 s45, 0, 0x1c000
	v_add_u32_e32 v168, s44, v149
	v_add_u32_e32 v184, s45, v149
	ds_read_b128 v[140:143], v168
	ds_read_b128 v[144:147], v168 offset:1024
	ds_read_b128 v[154:157], v168 offset:2048
	ds_read_b128 v[168:171], v168 offset:3072
	ds_read_b128 v[172:175], v184
	ds_read_b128 v[176:179], v184 offset:1024
	ds_read_b128 v[180:183], v184 offset:2048
	ds_read_b128 v[184:187], v184 offset:3072
	s_add_u32 s6, s6, s78
	s_addc_u32 s7, s7, 0
	s_mov_b32 m0, s30
	v_lshl_add_u64 v[248:249], s[6:7], 0, v[134:135]
	ds_read_b128 v[188:191], v153 offset:32768
	ds_read_b128 v[212:215], v153 offset:33792
	ds_read_b128 v[216:219], v153 offset:34816
	ds_read_b128 v[220:223], v153 offset:35840
	ds_read_b128 v[224:227], v153 offset:36864
	ds_read_b128 v[228:231], v153 offset:37888
	ds_read_b128 v[232:235], v153 offset:38912
	global_load_lds_dwordx4 v[248:249], off
	v_lshl_add_u64 v[248:249], s[6:7], 0, v[132:133]
	s_mov_b32 m0, s31
	ds_read_b128 v[236:239], v153 offset:39936
	global_load_lds_dwordx4 v[248:249], off
	s_waitcnt vmcnt(8)
	s_waitcnt lgkmcnt(0)
	s_barrier
	s_waitcnt lgkmcnt(0)
	v_mfma_f32_16x16x32_bf16 v[126:129], v[140:143], v[188:191], v[126:129]
	v_mfma_f32_16x16x32_bf16 v[122:125], v[154:157], v[188:191], v[122:125]
	v_mfma_f32_16x16x32_bf16 v[110:113], v[140:143], v[216:219], v[110:113]
	v_mfma_f32_16x16x32_bf16 v[106:109], v[154:157], v[216:219], v[106:109]
	v_mfma_f32_16x16x32_bf16 v[94:97], v[140:143], v[224:227], v[94:97]
	v_mfma_f32_16x16x32_bf16 v[90:93], v[154:157], v[224:227], v[90:93]
	v_mfma_f32_16x16x32_bf16 v[78:81], v[140:143], v[232:235], v[78:81]
	v_mfma_f32_16x16x32_bf16 v[74:77], v[154:157], v[232:235], v[74:77]
	v_mfma_f32_16x16x32_bf16 v[126:129], v[144:147], v[212:215], v[126:129]
	v_mfma_f32_16x16x32_bf16 v[122:125], v[168:171], v[212:215], v[122:125]
	v_mfma_f32_16x16x32_bf16 v[110:113], v[144:147], v[220:223], v[110:113]
	v_mfma_f32_16x16x32_bf16 v[106:109], v[168:171], v[220:223], v[106:109]
	v_mfma_f32_16x16x32_bf16 v[94:97], v[144:147], v[228:231], v[94:97]
	v_mfma_f32_16x16x32_bf16 v[90:93], v[168:171], v[228:231], v[90:93]
	v_mfma_f32_16x16x32_bf16 v[78:81], v[144:147], v[236:239], v[78:81]
	v_mfma_f32_16x16x32_bf16 v[74:77], v[168:171], v[236:239], v[74:77]
	v_mfma_f32_16x16x32_bf16 v[118:121], v[172:175], v[188:191], v[118:121]
	v_mfma_f32_16x16x32_bf16 v[114:117], v[180:183], v[188:191], v[114:117]
	v_mfma_f32_16x16x32_bf16 v[102:105], v[172:175], v[216:219], v[102:105]
	v_mfma_f32_16x16x32_bf16 v[98:101], v[180:183], v[216:219], v[98:101]
	v_mfma_f32_16x16x32_bf16 v[86:89], v[172:175], v[224:227], v[86:89]
	v_mfma_f32_16x16x32_bf16 v[82:85], v[180:183], v[224:227], v[82:85]
	v_mfma_f32_16x16x32_bf16 v[70:73], v[172:175], v[232:235], v[70:73]
	v_mfma_f32_16x16x32_bf16 v[66:69], v[180:183], v[232:235], v[66:69]
	v_mfma_f32_16x16x32_bf16 v[118:121], v[176:179], v[212:215], v[118:121]
	v_mfma_f32_16x16x32_bf16 v[114:117], v[184:187], v[212:215], v[114:117]
	v_mfma_f32_16x16x32_bf16 v[102:105], v[176:179], v[220:223], v[102:105]
	v_mfma_f32_16x16x32_bf16 v[98:101], v[184:187], v[220:223], v[98:101]
	v_mfma_f32_16x16x32_bf16 v[86:89], v[176:179], v[228:231], v[86:89]
	v_mfma_f32_16x16x32_bf16 v[82:85], v[184:187], v[228:231], v[82:85]
	v_mfma_f32_16x16x32_bf16 v[70:73], v[176:179], v[236:239], v[70:73]
	v_mfma_f32_16x16x32_bf16 v[66:69], v[184:187], v[236:239], v[66:69]
	s_barrier
; #define PG8_STAGE(bufoff, gbase, voff) do { _Pragma("unroll") for (int _i = 0; _i < 2; ++_i) \
;         __builtin_amdgcn_global_load_lds((const unsigned*)((const char*)(gbase) + (voff)[_i]), (PG8_LAS unsigned*)(lds + (bufoff) + ldsw + _i * 8192), 16, 0, 0); } while (0)
; #define PG8_LDA(dst, b, h) do { _Pragma("unroll") for (int m = 0; m < 4; ++m) _Pragma("unroll") for (int k = 0; k < 2; ++k) dst[m][k] = *(const PG8_LAS bf16x8*)(lds + PG8_SA(b, h) + aoff + m * 2048 + k * 1024); } while (0)
; #define PG8_MMA(ai, bj, At, Bt) do { __builtin_amdgcn_s_setprio(1); _Pragma("unroll") for (int m = 0; m < 4; ++m) _Pragma("unroll") for (int n = 0; n < 2; ++n) _Pragma("unroll") for (int k = 0; k < 2; ++k) \
;         acc[ai][bj][m][n] = __builtin_amdgcn_mfma_f32_16x16x32_bf16(Bt[n][k], At[m][k], acc[ai][bj][m][n], 0, 0, 0); __builtin_amdgcn_s_setprio(0); } while (0)
; #define PG8_WAIT_V(n) asm volatile("s_waitcnt vmcnt(" #n ")" ::: "memory")
; #define PG8_WAIT_L(n) asm volatile("s_waitcnt lgkmcnt(" #n ")" ::: "memory")
; #define PG8_BAR __builtin_amdgcn_s_barrier()
; #define PG8_SCHED __builtin_amdgcn_sched_barrier(0)
; template <class Epi, class Sched, bool ALIGN_EPI = false, bool SP2 = false>
; __device__ __forceinline__ void gemm_phase(PG8_LAS unsigned char* lds, const Gemm g, const Sched& S, const Epi& E, int wave_in) {
;     ...
;         for (int t = 0; t < nt; t += 2) {
;             const bool last = (t == nt - 2);
;             const char* a1 = cA + (size_t)(t + 1) * kstep;
;             const char* a2 = last ? nA : cA + (size_t)(t + 2) * kstep; const char* b2 = last ? nB : cB + (size_t)(t + 2) * kstep;
;             const char* a3 = a2 + kstep; const char* b3 = b2 + kstep;
;     ...
;             PG8_LDA(At, 1, 1); PG8_STAGE(PG8_SB(1, 0), b3, voffB); PG8_STAGE(PG8_SB(1, 1), b3 + hstep, voffB); PG8_STAGE(PG8_SA(1, 0), a3, voffA);
;             PG8_WAIT_V(8); PG8_WAIT_L(0); PG8_BAR; PG8_MMA(1, 0, At, B0); PG8_MMA(1, 1, At, B1); PG8_BAR; PG8_SCHED;
	s_add_i32 s6, s44, s27
	v_lshl_add_u64 v[192:193], v[192:193], 0, s[84:85]
	s_mov_b32 m0, s6
	ds_read_b128 v[188:191], v153 offset:49152
	ds_read_b128 v[212:215], v153 offset:50176
	ds_read_b128 v[216:219], v153 offset:51200
	ds_read_b128 v[220:223], v153 offset:52224
	global_load_lds_dwordx4 v[192:193], off
	v_lshl_add_u64 v[192:193], v[200:201], 0, s[84:85]
	s_add_i32 m0, s6, 0x2000
	s_add_i32 s6, s45, s27
	global_load_lds_dwordx4 v[192:193], off
	v_lshl_add_u64 v[192:193], v[240:241], 0, s[84:85]
	s_mov_b32 m0, s6
	ds_read_b128 v[224:227], v153 offset:53248
	global_load_lds_dwordx4 v[192:193], off
	v_lshl_add_u64 v[192:193], v[242:243], 0, s[84:85]
	s_add_i32 m0, s6, 0x2000
	ds_read_b128 v[228:231], v153 offset:54272
	global_load_lds_dwordx4 v[192:193], off
	v_lshl_add_u64 v[192:193], v[244:245], 0, s[84:85]
	s_mov_b32 m0, s34
	ds_read_b128 v[232:235], v153 offset:55296
	global_load_lds_dwordx4 v[192:193], off
	v_lshl_add_u64 v[192:193], v[246:247], 0, s[84:85]
	s_mov_b32 m0, s35
	ds_read_b128 v[236:239], v153 offset:56320
	global_load_lds_dwordx4 v[192:193], off
	s_waitcnt vmcnt(8)
	s_waitcnt lgkmcnt(0)
	s_barrier
	s_waitcnt lgkmcnt(0)
	v_mfma_f32_16x16x32_bf16 v[62:65], v[140:143], v[188:191], v[62:65]
	v_mfma_f32_16x16x32_bf16 v[58:61], v[154:157], v[188:191], v[58:61]
	v_mfma_f32_16x16x32_bf16 v[46:49], v[140:143], v[216:219], v[46:49]
	v_mfma_f32_16x16x32_bf16 v[42:45], v[154:157], v[216:219], v[42:45]
	v_mfma_f32_16x16x32_bf16 v[30:33], v[140:143], v[224:227], v[30:33]
	v_mfma_f32_16x16x32_bf16 v[26:29], v[154:157], v[224:227], v[26:29]
	v_mfma_f32_16x16x32_bf16 v[14:17], v[140:143], v[232:235], v[14:17]
	v_mfma_f32_16x16x32_bf16 v[10:13], v[154:157], v[232:235], v[10:13]
	v_mfma_f32_16x16x32_bf16 v[62:65], v[144:147], v[212:215], v[62:65]
	v_mfma_f32_16x16x32_bf16 v[58:61], v[168:171], v[212:215], v[58:61]
	v_mfma_f32_16x16x32_bf16 v[46:49], v[144:147], v[220:223], v[46:49]
	v_mfma_f32_16x16x32_bf16 v[42:45], v[168:171], v[220:223], v[42:45]
	v_mfma_f32_16x16x32_bf16 v[30:33], v[144:147], v[228:231], v[30:33]
	v_mfma_f32_16x16x32_bf16 v[26:29], v[168:171], v[228:231], v[26:29]
	v_mfma_f32_16x16x32_bf16 v[14:17], v[144:147], v[236:239], v[14:17]
	v_mfma_f32_16x16x32_bf16 v[10:13], v[168:171], v[236:239], v[10:13]
	v_mfma_f32_16x16x32_bf16 v[54:57], v[172:175], v[188:191], v[54:57]
	v_mfma_f32_16x16x32_bf16 v[50:53], v[180:183], v[188:191], v[50:53]
	v_mfma_f32_16x16x32_bf16 v[38:41], v[172:175], v[216:219], v[38:41]
	v_mfma_f32_16x16x32_bf16 v[34:37], v[180:183], v[216:219], v[34:37]
	v_mfma_f32_16x16x32_bf16 v[22:25], v[172:175], v[224:227], v[22:25]
	v_mfma_f32_16x16x32_bf16 v[18:21], v[180:183], v[224:227], v[18:21]
	v_mfma_f32_16x16x32_bf16 v[6:9], v[172:175], v[232:235], v[6:9]
	v_mfma_f32_16x16x32_bf16 v[2:5], v[180:183], v[232:235], v[2:5]
	v_mfma_f32_16x16x32_bf16 v[54:57], v[176:179], v[212:215], v[54:57]
	v_mfma_f32_16x16x32_bf16 v[50:53], v[184:187], v[212:215], v[50:53]
	v_mfma_f32_16x16x32_bf16 v[38:41], v[176:179], v[220:223], v[38:41]
	v_mfma_f32_16x16x32_bf16 v[34:37], v[184:187], v[220:223], v[34:37]
	v_mfma_f32_16x16x32_bf16 v[22:25], v[176:179], v[228:231], v[22:25]
	v_mfma_f32_16x16x32_bf16 v[18:21], v[184:187], v[228:231], v[18:21]
	v_mfma_f32_16x16x32_bf16 v[6:9], v[176:179], v[236:239], v[6:9]
	v_mfma_f32_16x16x32_bf16 v[2:5], v[184:187], v[236:239], v[2:5]
	s_barrier
	s_add_u32 s4, s4, 0x100
	s_addc_u32 s5, s5, 0
	s_add_u32 s24, s24, 0x100
	s_addc_u32 s25, s25, 0
	s_cmp_ge_u32 s43, s36
	s_mov_b32 s6, s43
	s_cbranch_scc0 .LBB0_404
	s_and_b64 vcc, exec, s[16:17]
	s_cbranch_vccz .LBB0_407
	s_barrier
